# v033
# baseline (speedup 1.0000x reference)
; #define ISSUE_K(t, slot) do { const char* kg_ = (const char*)(Kh + (long)(t) * (KVBLK * 192)); char* kl_ = K_lds + (slot) * SHM_K + tid * 16; \
;     DMA16(kg_ + kso0, kl_); DMA16(kg_ + kso1, kl_ + 8192); DMA16(kg_ + kso2, kl_ + 16384); } while (0)
; #define ISSUE_V(t, slot) do { const char* vg_ = (const char*)(Vh + (long)(t) * (KVBLK * 128)); char* vl_ = V_lds + (slot) * SHM_V + tid * 16; \
;     DMA16(vg_ + vso0, vl_); DMA16(vg_ + vso1, vl_ + 8192); } while (0)
; #define TBAR(n) do { asm volatile("s_waitcnt vmcnt(" #n ") lgkmcnt(0)" ::: "memory"); __builtin_amdgcn_s_barrier(); SBAR(); } while (0)
; __device__ __forceinline__ void qkt(f32x16& p0, f32x16& p1, const char* Ks, const bf16x8* qr, int r32, int hi) {
;     ...
;   for (int d0 = 0; d0 < 12; ++d0) { int cb = (d0 * 16 + hi * 8) * 2;
;     bf16x8 b0 = *reinterpret_cast<const bf16x8*>(Ks + KSWZ(r32, cb));
;     bf16x8 b1 = *reinterpret_cast<const bf16x8*>(Ks + KSWZ(32 + r32, cb));
;     p0 = __builtin_amdgcn_mfma_f32_32x32x16_bf16(b0, qr[d0], p0, 0, 0, 0);
;     p1 = __builtin_amdgcn_mfma_f32_32x32x16_bf16(b1, qr[d0], p1, 0, 0, 0); }
; __device__ __forceinline__ void attn_body(const u16* __restrict__ Qb, const u16* __restrict__ Kh, const u16* __restrict__ Vh,
;                                           u16* __restrict__ Ob, int seq, int wvs) {
;     ...
;     TBAR(5);
;     ISSUE_K(j + 2, NEXT3(NEXT3(sK))); ISSUE_V(j + 1, NEXT3(NEXT3(sV)));
;     qkt(pB0, pB1, K_lds + sK * SHM_K, qr, r32, hi);
;     finishSM(pA0, pA1, alA, l_reg, pa0, pa1, pa2, pa3);
;     pv_d0(o, vb0 + sV * SHM_V, pa0, pa1, pa2, pa3); partialSM(pB0, pB1, m_reg, mnB, alB);
.LBB0_331:
	s_waitcnt vmcnt(5) lgkmcnt(0)
	s_barrier
	s_add_i32 s4, s31, 1
	s_cmp_lg_u32 s31, 2
	s_cselect_b32 s13, s4, 0
	s_mul_i32 s15, s13, 0x6000
	s_add_i32 s10, s15, 0x6000
	s_cmp_eq_u32 s13, 2
	s_cselect_b64 s[4:5], -1, 0
	s_and_b64 s[8:9], s[4:5], exec
	s_cselect_b32 s8, 0, s10
	s_lshl_b32 vcc_lo, s69, 4
	s_add_i32 vcc_lo, vcc_lo, s8
	s_add_i32 vcc_hi, vcc_lo, 0xc000
	s_mov_b32 m0, vcc_hi
	s_add_i32 vcc_hi, vcc_lo, 0xe000
	global_load_lds_dwordx4 v166, s[98:99]
	s_mov_b32 m0, vcc_hi
	s_add_i32 vcc_hi, vcc_lo, 0x10000
	global_load_lds_dwordx4 v167, s[98:99]
	s_mov_b32 m0, vcc_hi
	s_add_i32 s8, s12, 1
	s_cmp_lg_u32 s12, 2
	s_cselect_b32 s16, s8, 0
	s_lshl_b32 s14, s16, 14
	s_add_i32 s17, s14, 0x4000
	s_cmp_eq_u32 s16, 2
	s_cselect_b64 s[8:9], -1, 0
	s_and_b64 s[10:11], s[8:9], exec
	s_cselect_b32 s10, 0, s17
	global_load_lds_dwordx4 v168, s[98:99]
	s_lshl_b32 vcc_lo, s69, 4
	s_add_i32 vcc_lo, vcc_lo, s10
	s_mov_b32 m0, vcc_lo
	s_add_i32 vcc_hi, vcc_lo, 0x2000
	global_load_lds_dwordx4 v169, s[100:101]
	s_mov_b32 m0, vcc_hi
	s_add_u32 s98, s98, 0x6000
	s_addc_u32 s99, s99, 0
	global_load_lds_dwordx4 v170, s[100:101]
	s_add_u32 s100, s100, 0x4000
	s_addc_u32 s101, s101, 0
	s_mul_i32 s10, s31, 0x6000
	s_add_i32 s10, s10, 0
	v_add_u32_e32 v162, s10, v193
	v_add_u32_e32 v253, s10, v199
	v_add_u32_e32 v252, s10, v200
	v_add_u32_e32 v244, s10, v202
	ds_read_b128 v[64:67], v162 offset:49152
	ds_read_b128 v[68:71], v162 offset:61440
	ds_read_b128 v[228:231], v253 offset:49152
	ds_read_b128 v[232:235], v253 offset:61440
	s_waitcnt lgkmcnt(2)
	v_mfma_f32_32x32x16_bf16 v[80:95], v[64:67], v[140:143], 0
	ds_read_b128 v[236:239], v252 offset:49152
	ds_read_b128 v[240:243], v252 offset:61440
	v_exp_f32_e32 v158, v158
	v_exp_f32_e32 v159, v159
	v_exp_f32_e32 v156, v156
	v_exp_f32_e32 v157, v157
	v_mfma_f32_32x32x16_bf16 v[64:79], v[68:71], v[140:143], 0
	v_exp_f32_e32 v154, v154
	v_exp_f32_e32 v155, v155
	v_exp_f32_e32 v163, v153
	v_exp_f32_e32 v206, v150
	v_exp_f32_e32 v227, v151
	v_cvt_pk_bf16_f32 v150, v214, v216
	v_cvt_pk_bf16_f32 v151, v217, v219
	s_waitcnt lgkmcnt(2)
	v_mfma_f32_32x32x16_bf16 v[64:79], v[232:235], v[136:139], v[64:79]
	v_cvt_pk_bf16_f32 v153, v156, v157
	v_mfma_f32_32x32x16_bf16 v[80:95], v[228:231], v[136:139], v[80:95]
	ds_read_b128 v[228:231], v244 offset:49152
	ds_read_b128 v[232:235], v244 offset:61440
	s_waitcnt lgkmcnt(2)
	v_mfma_f32_32x32x16_bf16 v[64:79], v[240:243], v[132:135], v[64:79]
	v_mfma_f32_32x32x16_bf16 v[80:95], v[236:239], v[132:135], v[80:95]
	ds_read_b128 v[236:239], v162 offset:49280
	ds_read_b128 v[240:243], v162 offset:61568
	s_waitcnt lgkmcnt(2)
	v_mfma_f32_32x32x16_bf16 v[64:79], v[232:235], v[128:131], v[64:79]
	v_mfma_f32_32x32x16_bf16 v[80:95], v[228:231], v[128:131], v[80:95]
	ds_read_b128 v[228:231], v253 offset:49280
	ds_read_b128 v[232:235], v253 offset:61568
	s_waitcnt lgkmcnt(2)
	v_mfma_f32_32x32x16_bf16 v[64:79], v[240:243], v[124:127], v[64:79]
	v_mfma_f32_32x32x16_bf16 v[80:95], v[236:239], v[124:127], v[80:95]
	ds_read_b128 v[236:239], v252 offset:49280
	ds_read_b128 v[240:243], v252 offset:61568
	s_waitcnt lgkmcnt(2)
	v_mfma_f32_32x32x16_bf16 v[64:79], v[232:235], v[120:123], v[64:79]
	v_mfma_f32_32x32x16_bf16 v[80:95], v[228:231], v[120:123], v[80:95]
	ds_read_b128 v[228:231], v244 offset:49280
	ds_read_b128 v[232:235], v244 offset:61568
	s_waitcnt lgkmcnt(2)
	v_mfma_f32_32x32x16_bf16 v[64:79], v[240:243], v[116:119], v[64:79]
	v_mfma_f32_32x32x16_bf16 v[80:95], v[236:239], v[116:119], v[80:95]
	ds_read_b128 v[236:239], v162 offset:49408
	ds_read_b128 v[240:243], v162 offset:61696
	s_waitcnt lgkmcnt(2)
	v_mfma_f32_32x32x16_bf16 v[64:79], v[232:235], v[112:115], v[64:79]
	v_mfma_f32_32x32x16_bf16 v[80:95], v[228:231], v[112:115], v[80:95]
	ds_read_b128 v[228:231], v253 offset:49408
	ds_read_b128 v[232:235], v253 offset:61696
	s_waitcnt lgkmcnt(2)
	v_mfma_f32_32x32x16_bf16 v[64:79], v[240:243], v[108:111], v[64:79]
	v_mfma_f32_32x32x16_bf16 v[80:95], v[236:239], v[108:111], v[80:95]
	ds_read_b128 v[236:239], v252 offset:49408
	ds_read_b128 v[240:243], v252 offset:61696
	s_waitcnt lgkmcnt(2)
	v_mfma_f32_32x32x16_bf16 v[64:79], v[232:235], v[104:107], v[64:79]
	v_mfma_f32_32x32x16_bf16 v[80:95], v[228:231], v[104:107], v[80:95]
	ds_read_b128 v[228:231], v244 offset:49408
	ds_read_b128 v[232:235], v244 offset:61696
	v_lshl_add_u32 v252, s12, 14, v190
	ds_read_b64_tr_b16 v[244:245], v252
	ds_read_b64_tr_b16 v[246:247], v252 offset:2048
	ds_read_b64_tr_b16 v[248:249], v252 offset:4096
	ds_read_b64_tr_b16 v[250:251], v252 offset:6144
	v_exp_f32_e32 v162, v152
	v_cvt_pk_bf16_f32 v152, v158, v159
	s_waitcnt lgkmcnt(6)
	v_mfma_f32_32x32x16_bf16 v[64:79], v[240:243], v[100:103], v[64:79]
	v_mfma_f32_32x32x16_bf16 v[80:95], v[236:239], v[100:103], v[80:95]
	s_waitcnt lgkmcnt(4)
; __device__ __forceinline__ void partialSM(f32x16& p0, f32x16& p1, float& m_reg, float& mn, float& alpha) {
;   constexpr float C = ASCALE * 1.4426950408889634f;
;   float pmax = p0[0]; for (int r = 1; r < 16; ++r) pmax = fmaxf(pmax, p0[r]); for (int r = 0; r < 16; ++r) pmax = fmaxf(pmax, p1[r]);
;   { auto rr = __builtin_amdgcn_permlane32_swap(__float_as_uint(pmax), __float_as_uint(pmax), false, false);
;     pmax = fmaxf(__uint_as_float(rr[0]), __uint_as_float(rr[1])); }
;   if (__builtin_expect(__all(pmax - m_reg <= THR / ASCALE), 1)) { mn = m_reg; alpha = 1.f; }
;   else { mn = fmaxf(m_reg, pmax); alpha = __builtin_amdgcn_exp2f((m_reg - mn) * C); m_reg = mn; }
;   float mnC = -mn * C;
;   for (int r = 0; r < 16; ++r) p0[r] = fmaf(p0[r], C, mnC); for (int r = 0; r < 16; ++r) p1[r] = fmaf(p1[r], C, mnC);
;   for (int r = 0; r < 16; ++r) p0[r] = __builtin_amdgcn_exp2f(p0[r]);
; }
; __device__ __forceinline__ void finishSM(f32x16& p0, f32x16& p1, float alpha, float& l_reg, bf16x8& pa0, bf16x8& pa1, bf16x8& pa2, bf16x8& pa3) {
;   for (int r = 0; r < 16; ++r) p1[r] = __builtin_amdgcn_exp2f(p1[r]);
;   float ps = 0; for (int r = 0; r < 16; ++r) ps += p0[r]; for (int r = 0; r < 16; ++r) ps += p1[r];
;   { auto rr = __builtin_amdgcn_permlane32_swap(__float_as_uint(ps), __float_as_uint(ps), false, false);
;     ps = __uint_as_float(rr[0]) + __uint_as_float(rr[1]); }
;   l_reg = l_reg * alpha + ps;
;     ...
;   PK4(p0, 0, pa0); PK4(p0, 8, pa1); PK4(p1, 0, pa2); PK4(p1, 8, pa3);
;     ...
; }
; __device__ __forceinline__ void qkt(f32x16& p0, f32x16& p1, const char* Ks, const bf16x8* qr, int r32, int hi) {
;   p0 = f32x16{}; p1 = f32x16{};
; #pragma unroll
;   for (int d0 = 0; d0 < 12; ++d0) { int cb = (d0 * 16 + hi * 8) * 2;
;     bf16x8 b0 = *reinterpret_cast<const bf16x8*>(Ks + KSWZ(r32, cb));
;     bf16x8 b1 = *reinterpret_cast<const bf16x8*>(Ks + KSWZ(32 + r32, cb));
;     p0 = __builtin_amdgcn_mfma_f32_32x32x16_bf16(b0, qr[d0], p0, 0, 0, 0);
;     p1 = __builtin_amdgcn_mfma_f32_32x32x16_bf16(b1, qr[d0], p1, 0, 0, 0); }
; }
; __device__ __forceinline__ int v_st(int k, int c) { const int kk = (k & ~0xC) | ((k & 4) << 1) | ((k & 8) >> 1); return ((kk >> 3) * 4 + (c >> 5)) * 512 + ((kk & 7) * 32 + (c & 31)) * 2; }
; __device__ __forceinline__ int v_rd_base(int lane) { return ((lane & 3) << 3) | (((lane >> 2) & 3) << 6) | (((lane >> 4) & 1) << 5) | (((lane >> 5) & 1) << 8); }
	v_mfma_f32_32x32x16_bf16 v[64:79], v[232:235], v[96:99], v[64:79]
	v_exp_f32_e32 v232, v144
	v_add_f32_e32 v144, v218, v220
	v_add_f32_e32 v144, v221, v144
	v_add_f32_e32 v144, v222, v144
	v_add_f32_e32 v144, v223, v144
	v_add_f32_e32 v144, v225, v144
	v_add_f32_e32 v144, v224, v144
	v_add_f32_e32 v144, v226, v144
	v_add_f32_e32 v144, v211, v144
	v_add_f32_e32 v144, v212, v144
	v_add_f32_e32 v144, v213, v144
	v_add_f32_e32 v144, v215, v144
	v_add_f32_e32 v144, v214, v144
	v_add_f32_e32 v144, v216, v144
	v_add_f32_e32 v144, v217, v144
	v_add_f32_e32 v144, v219, v144
	v_add_f32_e32 v144, v158, v144
	v_add_f32_e32 v144, v159, v144
	v_add_f32_e32 v144, v156, v144
	v_add_f32_e32 v144, v157, v144
	v_add_f32_e32 v144, v154, v144
	v_add_f32_e32 v144, v155, v144
	v_mfma_f32_32x32x16_bf16 v[80:95], v[228:231], v[96:99], v[80:95]
	v_exp_f32_e32 v228, v148
	v_add_f32_e32 v144, v162, v144
	v_exp_f32_e32 v229, v149
	v_add_f32_e32 v144, v163, v144
	v_exp_f32_e32 v230, v146
	v_add_f32_e32 v144, v206, v144
	v_exp_f32_e32 v231, v147
	v_add_f32_e32 v144, v227, v144
	v_add_f32_e32 v144, v228, v144
	v_exp_f32_e32 v233, v145
	v_add_f32_e32 v144, v229, v144
	v_add_f32_e32 v144, v230, v144
	v_add_f32_e32 v144, v231, v144
	v_add_f32_e32 v144, v232, v144
	v_add_f32_e32 v209, v233, v144
	v_cvt_pk_bf16_f32 v144, v218, v220
	v_cvt_pk_bf16_f32 v145, v221, v222
	v_cvt_pk_bf16_f32 v146, v223, v225
	v_cvt_pk_bf16_f32 v147, v224, v226
	s_nop 0
	v_cvt_pk_bf16_f32 v154, v154, v155
	v_cvt_pk_bf16_f32 v155, v162, v163
	v_cvt_pk_bf16_f32 v148, v211, v212
	v_cvt_pk_bf16_f32 v149, v213, v215
	v_cvt_pk_bf16_f32 v156, v206, v227
	ds_read_b64_tr_b16 v[220:221], v252 offset:8192
	ds_read_b64_tr_b16 v[222:223], v252 offset:10240
	ds_read_b64_tr_b16 v[224:225], v252 offset:12288
	ds_read_b64_tr_b16 v[226:227], v252 offset:14336
	s_waitcnt lgkmcnt(4)
	v_mfma_f32_32x32x16_bf16 v[0:15], v[144:147], v[244:247], v[0:15]
	ds_read_b64_tr_b16 v[212:213], v252 offset:512
	ds_read_b64_tr_b16 v[214:215], v252 offset:2560
	v_mfma_f32_32x32x16_bf16 v[0:15], v[148:151], v[248:251], v[0:15]
	ds_read_b64_tr_b16 v[216:217], v252 offset:4608
	ds_read_b64_tr_b16 v[218:219], v252 offset:6656
	v_cvt_pk_bf16_f32 v157, v228, v229
	v_cvt_pk_bf16_f32 v158, v230, v231
	v_cvt_pk_bf16_f32 v159, v232, v233
	s_nop 0
	s_waitcnt lgkmcnt(6)
	v_mfma_f32_32x32x16_bf16 v[0:15], v[152:155], v[220:223], v[0:15]
	ds_read_b64_tr_b16 v[220:221], v252 offset:8704
	ds_read_b64_tr_b16 v[222:223], v252 offset:10752
	v_mov_b32_e32 v210, v209
	s_nop 1
	v_permlane32_swap_b32_e32 v209, v210
	v_mov_b32_e32 v211, 1.0
	s_waitcnt lgkmcnt(6)
	v_mfma_f32_32x32x16_bf16 v[0:15], v[156:159], v[224:227], v[0:15]
	ds_read_b64_tr_b16 v[224:225], v252 offset:12800
	ds_read_b64_tr_b16 v[226:227], v252 offset:14848
	s_waitcnt lgkmcnt(6)
	v_mfma_f32_32x32x16_bf16 v[48:63], v[144:147], v[212:215], v[48:63]
	ds_read_b64_tr_b16 v[212:213], v252 offset:1024
	ds_read_b64_tr_b16 v[214:215], v252 offset:3072
	s_waitcnt lgkmcnt(6)
	v_mfma_f32_32x32x16_bf16 v[48:63], v[148:151], v[216:219], v[48:63]
	ds_read_b64_tr_b16 v[216:217], v252 offset:5120
	ds_read_b64_tr_b16 v[218:219], v252 offset:7168
	s_waitcnt lgkmcnt(6)
	v_mfma_f32_32x32x16_bf16 v[48:63], v[152:155], v[220:223], v[48:63]
	ds_read_b64_tr_b16 v[220:221], v252 offset:9216
	ds_read_b64_tr_b16 v[222:223], v252 offset:11264
	s_waitcnt lgkmcnt(6)
	v_mfma_f32_32x32x16_bf16 v[48:63], v[156:159], v[224:227], v[48:63]
	ds_read_b64_tr_b16 v[224:225], v252 offset:13312
	ds_read_b64_tr_b16 v[226:227], v252 offset:15360
	s_waitcnt lgkmcnt(6)
	v_mfma_f32_32x32x16_bf16 v[32:47], v[144:147], v[212:215], v[32:47]
	ds_read_b64_tr_b16 v[212:213], v252 offset:1536
	ds_read_b64_tr_b16 v[214:215], v252 offset:3584
	s_waitcnt lgkmcnt(6)
	v_mfma_f32_32x32x16_bf16 v[32:47], v[148:151], v[216:219], v[32:47]
	ds_read_b64_tr_b16 v[216:217], v252 offset:5632
	ds_read_b64_tr_b16 v[218:219], v252 offset:7680
	s_waitcnt lgkmcnt(6)
	v_mfma_f32_32x32x16_bf16 v[32:47], v[152:155], v[220:223], v[32:47]
	ds_read_b64_tr_b16 v[220:221], v252 offset:9728
	ds_read_b64_tr_b16 v[222:223], v252 offset:11776
	s_waitcnt lgkmcnt(6)
	v_mfma_f32_32x32x16_bf16 v[32:47], v[156:159], v[224:227], v[32:47]
	ds_read_b64_tr_b16 v[224:225], v252 offset:13824
	ds_read_b64_tr_b16 v[226:227], v252 offset:15872
	s_waitcnt lgkmcnt(6)
	v_mfma_f32_32x32x16_bf16 v[16:31], v[144:147], v[212:215], v[16:31]
	v_max_f32_e32 v144, v80, v81
	v_max3_f32 v144, v144, v82, v83
	v_max3_f32 v144, v144, v84, v85
	v_max3_f32 v144, v144, v86, v87
	v_max3_f32 v144, v144, v88, v89
	s_waitcnt lgkmcnt(4)
	v_mfma_f32_32x32x16_bf16 v[16:31], v[148:151], v[216:219], v[16:31]
	v_max3_f32 v144, v144, v90, v91
	v_max3_f32 v144, v144, v92, v93
	v_max3_f32 v144, v144, v94, v95
	v_max3_f32 v144, v144, v64, v65
	v_max3_f32 v144, v144, v66, v67
	v_max3_f32 v144, v144, v68, v69
	v_max3_f32 v144, v144, v70, v71
	s_waitcnt lgkmcnt(2)
	v_mfma_f32_32x32x16_bf16 v[16:31], v[152:155], v[220:223], v[16:31]
	v_max3_f32 v144, v144, v72, v73
	v_max3_f32 v144, v144, v74, v75
	v_max3_f32 v144, v144, v76, v77
	v_max3_f32 v144, v144, v78, v79
	v_mov_b32_e32 v145, v144
	s_nop 1
	v_permlane32_swap_b32_e32 v144, v145
	s_waitcnt lgkmcnt(0)
	v_mfma_f32_32x32x16_bf16 v[16:31], v[156:159], v[224:227], v[16:31]
	v_max_f32_e32 v144, v144, v145
	v_sub_f32_e32 v145, v144, v191
	v_cmp_ge_f32_e32 vcc, s35, v145
	s_cmp_eq_u64 vcc, exec
	s_cbranch_scc0 .LBB0_344
	v_cmp_gt_f32_e32 vcc, 1.0, v211
	s_cbranch_vccz .LBB0_336

; #define ISSUE_K(t, slot) do { const char* kg_ = (const char*)(Kh + (long)(t) * (KVBLK * 192)); char* kl_ = K_lds + (slot) * SHM_K + tid * 16; \
;     DMA16(kg_ + kso0, kl_); DMA16(kg_ + kso1, kl_ + 8192); DMA16(kg_ + kso2, kl_ + 16384); } while (0)
; #define ISSUE_V(t, slot) do { const char* vg_ = (const char*)(Vh + (long)(t) * (KVBLK * 128)); char* vl_ = V_lds + (slot) * SHM_V + tid * 16; \
;     DMA16(vg_ + vso0, vl_); DMA16(vg_ + vso1, vl_ + 8192); } while (0)
; #define TBAR(n) do { asm volatile("s_waitcnt vmcnt(" #n ") lgkmcnt(0)" ::: "memory"); __builtin_amdgcn_s_barrier(); SBAR(); } while (0)
; __device__ __forceinline__ void partialSM(f32x16& p0, f32x16& p1, float& m_reg, float& mn, float& alpha) {
;     ...
;   for (int r = 0; r < 16; ++r) p0[r] = fmaf(p0[r], C, mnC); for (int r = 0; r < 16; ++r) p1[r] = fmaf(p1[r], C, mnC);
;   for (int r = 0; r < 16; ++r) p0[r] = __builtin_amdgcn_exp2f(p0[r]);
; __device__ __forceinline__ void attn_body(const u16* __restrict__ Qb, const u16* __restrict__ Kh, const u16* __restrict__ Vh,
;                                           u16* __restrict__ Ob, int seq, int wvs) {
;     ...
;     TBAR(5);
;     if (j + 3 < NT) ISSUE_K(j + 3, NEXT3(NEXT3(sK)));
;     ISSUE_V(j + 2, NEXT3(NEXT3(sV)));
;     qkt(pA0, pA1, K_lds + sK * SHM_K, qr, r32, hi);
;     finishSM(pB0, pB1, alB, l_reg, pa0, pa1, pa2, pa3);
;     pv_d0(o, vb0 + sV * SHM_V, pa0, pa1, pa2, pa3); partialSM(pA0, pA1, m_reg, mnA, alA);
.LBB0_338:
	s_add_u32 s98, s98, 0x6000
	s_addc_u32 s99, s99, 0
	s_add_i32 s16, s16, 1
	s_and_b64 s[8:9], s[8:9], exec
	s_cselect_b32 s12, 0, s16
	s_lshl_b32 s17, s12, 14
	s_add_i32 s8, s17, 0x4000
	s_cmp_lg_u32 s12, 2
	v_mul_f32_e32 v180, 0xbdd53b94, v191
	s_cselect_b32 s16, s8, 0
	v_fmamk_f32 v221, v66, 0x3dd53b94, v180
	v_fmamk_f32 v219, v64, 0x3dd53b94, v180
	v_fmamk_f32 v220, v65, 0x3dd53b94, v180
	s_lshl_b32 vcc_lo, s69, 4
	s_add_i32 vcc_lo, vcc_lo, s16
	s_mov_b32 m0, vcc_lo
	s_add_i32 vcc_hi, vcc_lo, 0x2000
	global_load_lds_dwordx4 v169, s[100:101]
	s_mov_b32 m0, vcc_hi
	s_add_i32 s8, s15, 0
	v_fmamk_f32 v218, v68, 0x3dd53b94, v180
	global_load_lds_dwordx4 v170, s[100:101]
	s_add_u32 s100, s100, 0x4000
	s_addc_u32 s101, s101, 0
	v_add_u32_e32 v68, s8, v193
	v_fmamk_f32 v217, v67, 0x3dd53b94, v180
	v_fmamk_f32 v181, v69, 0x3dd53b94, v180
	v_fmamk_f32 v182, v70, 0x3dd53b94, v180
	v_fmamk_f32 v183, v71, 0x3dd53b94, v180
	ds_read_b128 v[64:67], v68 offset:49152
	ds_read_b128 v[68:71], v68 offset:61440
	v_add_u32_e32 v162, s8, v193
	v_add_u32_e32 v253, s8, v199
	v_add_u32_e32 v252, s8, v200
	v_add_u32_e32 v244, s8, v202
	ds_read_b128 v[176:179], v253 offset:49152
	ds_read_b128 v[222:225], v253 offset:61440
	v_fmamk_f32 v80, v80, 0x3dd53b94, v180
	v_fmamk_f32 v81, v81, 0x3dd53b94, v180
	v_fmamk_f32 v82, v82, 0x3dd53b94, v180
	v_fmamk_f32 v83, v83, 0x3dd53b94, v180
	v_fmamk_f32 v84, v84, 0x3dd53b94, v180
	v_fmamk_f32 v85, v85, 0x3dd53b94, v180
	v_fmamk_f32 v86, v86, 0x3dd53b94, v180
	v_fmamk_f32 v87, v87, 0x3dd53b94, v180
	v_fmamk_f32 v88, v88, 0x3dd53b94, v180
	v_fmamk_f32 v89, v89, 0x3dd53b94, v180
	v_fmamk_f32 v90, v90, 0x3dd53b94, v180
	v_fmamk_f32 v91, v91, 0x3dd53b94, v180
	v_fmamk_f32 v92, v92, 0x3dd53b94, v180
	v_fmamk_f32 v93, v93, 0x3dd53b94, v180
	v_fmamk_f32 v94, v94, 0x3dd53b94, v180
	v_fmamk_f32 v95, v95, 0x3dd53b94, v180
	v_exp_f32_e32 v144, v80
	v_exp_f32_e32 v145, v81
	v_exp_f32_e32 v146, v82
	v_exp_f32_e32 v156, v83
	v_exp_f32_e32 v147, v84
	v_exp_f32_e32 v157, v85
	v_exp_f32_e32 v158, v86
	v_exp_f32_e32 v159, v87
	v_exp_f32_e32 v148, v88
	v_exp_f32_e32 v150, v89
	v_exp_f32_e32 v149, v90
	v_exp_f32_e32 v151, v91
	v_exp_f32_e32 v152, v92
	v_exp_f32_e32 v153, v93
	v_exp_f32_e32 v154, v94
	v_exp_f32_e32 v155, v95
	s_waitcnt lgkmcnt(2)
	v_mfma_f32_32x32x16_bf16 v[80:95], v[64:67], v[140:143], 0
	ds_read_b128 v[236:239], v252 offset:49152
	ds_read_b128 v[240:243], v252 offset:61440
	v_fmamk_f32 v184, v72, 0x3dd53b94, v180
	v_fmamk_f32 v185, v73, 0x3dd53b94, v180
	v_fmamk_f32 v212, v74, 0x3dd53b94, v180
	v_fmamk_f32 v213, v75, 0x3dd53b94, v180
	v_fmamk_f32 v214, v76, 0x3dd53b94, v180
	v_fmamk_f32 v215, v77, 0x3dd53b94, v180
	v_fmamk_f32 v216, v78, 0x3dd53b94, v180
	v_fmac_f32_e32 v180, 0x3dd53b94, v79
	v_mfma_f32_32x32x16_bf16 v[64:79], v[68:71], v[140:143], 0
	v_exp_f32_e32 v163, v220
	v_exp_f32_e32 v206, v218
	v_exp_f32_e32 v181, v181
	v_exp_f32_e32 v182, v182
	v_exp_f32_e32 v183, v183
	s_waitcnt lgkmcnt(2)
	v_mfma_f32_32x32x16_bf16 v[80:95], v[176:179], v[136:139], v[80:95]
	v_exp_f32_e32 v184, v184
	v_exp_f32_e32 v185, v185
	v_exp_f32_e32 v212, v212
	v_exp_f32_e32 v213, v213
	v_exp_f32_e32 v214, v214
	v_exp_f32_e32 v215, v215
	v_exp_f32_e32 v216, v216
	v_mfma_f32_32x32x16_bf16 v[64:79], v[222:225], v[136:139], v[64:79]
	ds_read_b128 v[176:179], v244 offset:49152
	ds_read_b128 v[222:225], v244 offset:61440
	v_exp_f32_e32 v180, v180
	s_waitcnt lgkmcnt(2)
	v_mfma_f32_32x32x16_bf16 v[80:95], v[236:239], v[132:135], v[80:95]
	v_mfma_f32_32x32x16_bf16 v[64:79], v[240:243], v[132:135], v[64:79]
	ds_read_b128 v[236:239], v162 offset:49280
	ds_read_b128 v[240:243], v162 offset:61568
	s_waitcnt lgkmcnt(2)
	v_mfma_f32_32x32x16_bf16 v[80:95], v[176:179], v[128:131], v[80:95]
	v_mfma_f32_32x32x16_bf16 v[64:79], v[222:225], v[128:131], v[64:79]
	ds_read_b128 v[176:179], v253 offset:49280
	ds_read_b128 v[222:225], v253 offset:61568
	s_waitcnt lgkmcnt(2)
	v_mfma_f32_32x32x16_bf16 v[80:95], v[236:239], v[124:127], v[80:95]
	v_mfma_f32_32x32x16_bf16 v[64:79], v[240:243], v[124:127], v[64:79]
	ds_read_b128 v[236:239], v252 offset:49280
	ds_read_b128 v[240:243], v252 offset:61568
	s_waitcnt lgkmcnt(2)
	v_mfma_f32_32x32x16_bf16 v[80:95], v[176:179], v[120:123], v[80:95]
	v_mfma_f32_32x32x16_bf16 v[64:79], v[222:225], v[120:123], v[64:79]
	ds_read_b128 v[176:179], v244 offset:49280
	ds_read_b128 v[222:225], v244 offset:61568
	s_waitcnt lgkmcnt(2)
	v_mfma_f32_32x32x16_bf16 v[80:95], v[236:239], v[116:119], v[80:95]
	v_mfma_f32_32x32x16_bf16 v[64:79], v[240:243], v[116:119], v[64:79]
	ds_read_b128 v[236:239], v162 offset:49408
	ds_read_b128 v[240:243], v162 offset:61696
	s_waitcnt lgkmcnt(2)
	v_mfma_f32_32x32x16_bf16 v[80:95], v[176:179], v[112:115], v[80:95]
	v_mfma_f32_32x32x16_bf16 v[64:79], v[222:225], v[112:115], v[64:79]
	ds_read_b128 v[176:179], v253 offset:49408
	ds_read_b128 v[222:225], v253 offset:61696
	s_waitcnt lgkmcnt(2)
	v_mfma_f32_32x32x16_bf16 v[80:95], v[236:239], v[108:111], v[80:95]
	v_mfma_f32_32x32x16_bf16 v[64:79], v[240:243], v[108:111], v[64:79]
	ds_read_b128 v[236:239], v252 offset:49408
	ds_read_b128 v[240:243], v252 offset:61696
	s_waitcnt lgkmcnt(2)
	v_mfma_f32_32x32x16_bf16 v[80:95], v[176:179], v[104:107], v[80:95]
	v_mfma_f32_32x32x16_bf16 v[64:79], v[222:225], v[104:107], v[64:79]
	ds_read_b128 v[176:179], v244 offset:49408
	ds_read_b128 v[222:225], v244 offset:61696
	v_add_u32_e32 v252, s14, v190
	ds_read_b64_tr_b16 v[244:245], v252
	ds_read_b64_tr_b16 v[246:247], v252 offset:2048
	ds_read_b64_tr_b16 v[248:249], v252 offset:4096
	ds_read_b64_tr_b16 v[250:251], v252 offset:6144
	v_exp_f32_e32 v162, v219
	s_waitcnt lgkmcnt(6)
; __device__ __forceinline__ void partialSM(f32x16& p0, f32x16& p1, float& m_reg, float& mn, float& alpha) {
;   constexpr float C = ASCALE * 1.4426950408889634f;
;   float pmax = p0[0]; for (int r = 1; r < 16; ++r) pmax = fmaxf(pmax, p0[r]); for (int r = 0; r < 16; ++r) pmax = fmaxf(pmax, p1[r]);
;   { auto rr = __builtin_amdgcn_permlane32_swap(__float_as_uint(pmax), __float_as_uint(pmax), false, false);
;     pmax = fmaxf(__uint_as_float(rr[0]), __uint_as_float(rr[1])); }
;   if (__builtin_expect(__all(pmax - m_reg <= THR / ASCALE), 1)) { mn = m_reg; alpha = 1.f; }
;   else { mn = fmaxf(m_reg, pmax); alpha = __builtin_amdgcn_exp2f((m_reg - mn) * C); m_reg = mn; }
;   float mnC = -mn * C;
;   for (int r = 0; r < 16; ++r) p0[r] = fmaf(p0[r], C, mnC); for (int r = 0; r < 16; ++r) p1[r] = fmaf(p1[r], C, mnC);
;   for (int r = 0; r < 16; ++r) p0[r] = __builtin_amdgcn_exp2f(p0[r]);
; }
; __device__ __forceinline__ void finishSM(f32x16& p0, f32x16& p1, float alpha, float& l_reg, bf16x8& pa0, bf16x8& pa1, bf16x8& pa2, bf16x8& pa3) {
;   for (int r = 0; r < 16; ++r) p1[r] = __builtin_amdgcn_exp2f(p1[r]);
;   float ps = 0; for (int r = 0; r < 16; ++r) ps += p0[r]; for (int r = 0; r < 16; ++r) ps += p1[r];
;   { auto rr = __builtin_amdgcn_permlane32_swap(__float_as_uint(ps), __float_as_uint(ps), false, false);
;     ps = __uint_as_float(rr[0]) + __uint_as_float(rr[1]); }
;   l_reg = l_reg * alpha + ps;
;     ...
;   PK4(p0, 0, pa0); PK4(p0, 8, pa1); PK4(p1, 0, pa2); PK4(p1, 8, pa3);
;     ...
; }
; __device__ __forceinline__ void qkt(f32x16& p0, f32x16& p1, const char* Ks, const bf16x8* qr, int r32, int hi) {
;   p0 = f32x16{}; p1 = f32x16{};
; #pragma unroll
;   for (int d0 = 0; d0 < 12; ++d0) { int cb = (d0 * 16 + hi * 8) * 2;
;     bf16x8 b0 = *reinterpret_cast<const bf16x8*>(Ks + KSWZ(r32, cb));
;     bf16x8 b1 = *reinterpret_cast<const bf16x8*>(Ks + KSWZ(32 + r32, cb));
;     p0 = __builtin_amdgcn_mfma_f32_32x32x16_bf16(b0, qr[d0], p0, 0, 0, 0);
;     p1 = __builtin_amdgcn_mfma_f32_32x32x16_bf16(b1, qr[d0], p1, 0, 0, 0); }
; }
; __device__ __forceinline__ int v_st(int k, int c) { const int kk = (k & ~0xC) | ((k & 4) << 1) | ((k & 8) >> 1); return ((kk >> 3) * 4 + (c >> 5)) * 512 + ((kk & 7) * 32 + (c & 31)) * 2; }
; __device__ __forceinline__ int v_rd_base(int lane) { return ((lane & 3) << 3) | (((lane >> 2) & 3) << 6) | (((lane >> 4) & 1) << 5) | (((lane >> 5) & 1) << 8); }
	v_mfma_f32_32x32x16_bf16 v[80:95], v[236:239], v[100:103], v[80:95]
	v_mfma_f32_32x32x16_bf16 v[64:79], v[240:243], v[100:103], v[64:79]
	s_waitcnt lgkmcnt(4)
	v_mfma_f32_32x32x16_bf16 v[80:95], v[176:179], v[96:99], v[80:95]
	v_add_f32_e32 v177, v144, v145
	v_add_f32_e32 v177, v146, v177
	v_add_f32_e32 v177, v156, v177
	v_add_f32_e32 v177, v147, v177
	v_add_f32_e32 v177, v157, v177
	v_add_f32_e32 v177, v158, v177
	v_add_f32_e32 v177, v159, v177
	v_add_f32_e32 v177, v148, v177
	v_add_f32_e32 v177, v150, v177
	v_add_f32_e32 v177, v149, v177
	v_add_f32_e32 v177, v151, v177
	v_add_f32_e32 v177, v152, v177
	v_add_f32_e32 v177, v153, v177
	v_exp_f32_e32 v176, v221
	v_add_f32_e32 v177, v154, v177
	v_exp_f32_e32 v179, v217
	v_add_f32_e32 v177, v155, v177
	v_add_f32_e32 v177, v162, v177
	v_add_f32_e32 v177, v163, v177
	v_add_f32_e32 v177, v176, v177
	v_add_f32_e32 v177, v179, v177
	v_add_f32_e32 v177, v206, v177
	v_add_f32_e32 v177, v181, v177
	v_add_f32_e32 v177, v182, v177
	v_add_f32_e32 v177, v183, v177
	v_add_f32_e32 v177, v184, v177
	v_add_f32_e32 v177, v185, v177
	v_cvt_pk_bf16_f32 v144, v144, v145
	v_cvt_pk_bf16_f32 v145, v146, v156
	v_cvt_pk_bf16_f32 v146, v147, v157
	v_cvt_pk_bf16_f32 v147, v158, v159
	v_add_f32_e32 v177, v212, v177
	v_add_f32_e32 v177, v213, v177
	v_add_f32_e32 v177, v214, v177
	v_add_f32_e32 v177, v215, v177
	v_add_f32_e32 v177, v216, v177
	v_cvt_pk_bf16_f32 v148, v148, v150
	v_cvt_pk_bf16_f32 v150, v152, v153
	v_cvt_pk_bf16_f32 v152, v162, v163
	v_mfma_f32_32x32x16_bf16 v[64:79], v[222:225], v[96:99], v[64:79]
	v_add_f32_e32 v177, v180, v177
	v_cvt_pk_bf16_f32 v149, v149, v151
	v_cvt_pk_bf16_f32 v151, v154, v155
	v_cvt_pk_bf16_f32 v154, v206, v181
	v_cvt_pk_bf16_f32 v155, v182, v183
	v_cvt_pk_bf16_f32 v157, v212, v213
	v_cvt_pk_bf16_f32 v158, v214, v215
	v_cvt_pk_bf16_f32 v159, v216, v180
	ds_read_b64_tr_b16 v[216:217], v252 offset:8192
	ds_read_b64_tr_b16 v[218:219], v252 offset:10240
	ds_read_b64_tr_b16 v[220:221], v252 offset:12288
	ds_read_b64_tr_b16 v[222:223], v252 offset:14336
	s_waitcnt lgkmcnt(4)
	v_mfma_f32_32x32x16_bf16 v[0:15], v[144:147], v[244:247], v[0:15]
	ds_read_b64_tr_b16 v[180:181], v252 offset:512
	ds_read_b64_tr_b16 v[182:183], v252 offset:2560
	v_cvt_pk_bf16_f32 v153, v176, v179
	v_mfma_f32_32x32x16_bf16 v[0:15], v[148:151], v[248:251], v[0:15]
	ds_read_b64_tr_b16 v[212:213], v252 offset:4608
	ds_read_b64_tr_b16 v[214:215], v252 offset:6656
	v_cvt_pk_bf16_f32 v156, v184, v185
	s_nop 1
	s_waitcnt lgkmcnt(6)
	v_mfma_f32_32x32x16_bf16 v[0:15], v[152:155], v[216:219], v[0:15]
	ds_read_b64_tr_b16 v[216:217], v252 offset:8704
	ds_read_b64_tr_b16 v[218:219], v252 offset:10752
	v_mov_b32_e32 v178, v177
	s_nop 1
	v_permlane32_swap_b32_e32 v177, v178
	s_waitcnt lgkmcnt(6)
	v_mfma_f32_32x32x16_bf16 v[0:15], v[156:159], v[220:223], v[0:15]
	ds_read_b64_tr_b16 v[220:221], v252 offset:12800
	ds_read_b64_tr_b16 v[222:223], v252 offset:14848
	s_waitcnt lgkmcnt(6)
	v_mfma_f32_32x32x16_bf16 v[48:63], v[144:147], v[180:183], v[48:63]
	ds_read_b64_tr_b16 v[180:181], v252 offset:1024
	ds_read_b64_tr_b16 v[182:183], v252 offset:3072
	s_waitcnt lgkmcnt(6)
	v_mfma_f32_32x32x16_bf16 v[48:63], v[148:151], v[212:215], v[48:63]
	ds_read_b64_tr_b16 v[212:213], v252 offset:5120
	ds_read_b64_tr_b16 v[214:215], v252 offset:7168
	s_waitcnt lgkmcnt(6)
	v_mfma_f32_32x32x16_bf16 v[48:63], v[152:155], v[216:219], v[48:63]
	ds_read_b64_tr_b16 v[216:217], v252 offset:9216
	ds_read_b64_tr_b16 v[218:219], v252 offset:11264
	s_waitcnt lgkmcnt(6)
	v_mfma_f32_32x32x16_bf16 v[48:63], v[156:159], v[220:223], v[48:63]
	ds_read_b64_tr_b16 v[220:221], v252 offset:13312
	ds_read_b64_tr_b16 v[222:223], v252 offset:15360
	s_waitcnt lgkmcnt(6)
	v_mfma_f32_32x32x16_bf16 v[32:47], v[144:147], v[180:183], v[32:47]
	ds_read_b64_tr_b16 v[180:181], v252 offset:1536
	ds_read_b64_tr_b16 v[182:183], v252 offset:3584
	s_waitcnt lgkmcnt(6)
	v_mfma_f32_32x32x16_bf16 v[32:47], v[148:151], v[212:215], v[32:47]
	ds_read_b64_tr_b16 v[212:213], v252 offset:5632
	ds_read_b64_tr_b16 v[214:215], v252 offset:7680
	s_waitcnt lgkmcnt(6)
	v_mfma_f32_32x32x16_bf16 v[32:47], v[152:155], v[216:219], v[32:47]
	ds_read_b64_tr_b16 v[216:217], v252 offset:9728
	ds_read_b64_tr_b16 v[218:219], v252 offset:11776
	s_waitcnt lgkmcnt(6)
	v_mfma_f32_32x32x16_bf16 v[32:47], v[156:159], v[220:223], v[32:47]
	ds_read_b64_tr_b16 v[220:221], v252 offset:13824
	ds_read_b64_tr_b16 v[222:223], v252 offset:15872
	s_waitcnt lgkmcnt(6)
	v_mfma_f32_32x32x16_bf16 v[16:31], v[144:147], v[180:183], v[16:31]
	v_max_f32_e32 v144, v80, v81
	v_max3_f32 v144, v144, v82, v83
	v_max3_f32 v144, v144, v84, v85
	v_max3_f32 v144, v144, v86, v87
	v_max3_f32 v144, v144, v88, v89
	v_max3_f32 v144, v144, v90, v91
	v_max3_f32 v144, v144, v92, v93
	s_waitcnt lgkmcnt(4)
	v_mfma_f32_32x32x16_bf16 v[16:31], v[148:151], v[212:215], v[16:31]
	v_max3_f32 v144, v144, v94, v95
	v_max3_f32 v144, v144, v64, v65
	v_max3_f32 v144, v144, v66, v67
	v_max3_f32 v144, v144, v68, v69
	v_max3_f32 v144, v144, v70, v71
	v_max3_f32 v144, v144, v72, v73
	v_max3_f32 v144, v144, v74, v75
	v_max3_f32 v144, v144, v76, v77
	s_waitcnt lgkmcnt(2)
	v_mfma_f32_32x32x16_bf16 v[16:31], v[152:155], v[216:219], v[16:31]
	v_max3_f32 v144, v144, v78, v79
	v_mov_b32_e32 v145, v144
	s_nop 1
	v_permlane32_swap_b32_e32 v144, v145
	v_max_f32_e32 v144, v144, v145
	v_sub_f32_e32 v145, v144, v191
	v_cmp_ge_f32_e32 vcc, s35, v145
	v_max_f32_e32 v144, v191, v144
	s_waitcnt lgkmcnt(0)
	v_mfma_f32_32x32x16_bf16 v[16:31], v[156:159], v[220:223], v[16:31]
	v_sub_f32_e32 v145, v191, v144
	v_mul_f32_e32 v145, 0x3dd53b94, v145
	v_exp_f32_e32 v145, v145
	s_cmp_eq_u64 vcc, exec
	s_cselect_b64 s[8:9], -1, 0
	v_cndmask_b32_e64 v176, v145, 1.0, s[8:9]
	v_cmp_gt_f32_e32 vcc, 1.0, v176
	s_cbranch_vccz .LBB0_342
	s_and_saveexec_b64 s[14:15], s[6:7]
	ds_write_b32 v188, v176 offset:128
	s_or_b64 exec, exec, s[14:15]
	s_waitcnt lgkmcnt(0)
	v_add_u32_e32 v145, v165, v160
	ds_read_b128 v[146:149], v145 offset:224
	ds_read_b128 v[150:153], v145 offset:192
	ds_read_b128 v[154:157], v145 offset:160
	ds_read_b128 v[180:183], v145 offset:128
	s_waitcnt lgkmcnt(0)
	v_pk_mul_f32 v[12:13], v[12:13], v[146:147]
	v_pk_mul_f32 v[8:9], v[8:9], v[150:151]
	v_pk_mul_f32 v[4:5], v[4:5], v[154:155]
	v_pk_mul_f32 v[14:15], v[14:15], v[148:149]
	v_pk_mul_f32 v[10:11], v[10:11], v[152:153]
	v_pk_mul_f32 v[6:7], v[6:7], v[156:157]
	v_pk_mul_f32 v[2:3], v[2:3], v[182:183]
	v_pk_mul_f32 v[0:1], v[0:1], v[180:181]
	v_pk_mul_f32 v[60:61], v[60:61], v[146:147]
	v_pk_mul_f32 v[56:57], v[56:57], v[150:151]
	v_pk_mul_f32 v[52:53], v[52:53], v[154:155]
	v_pk_mul_f32 v[62:63], v[62:63], v[148:149]
	v_pk_mul_f32 v[58:59], v[58:59], v[152:153]
	v_pk_mul_f32 v[54:55], v[54:55], v[156:157]
	v_pk_mul_f32 v[50:51], v[50:51], v[182:183]
	v_pk_mul_f32 v[48:49], v[48:49], v[180:181]
	v_pk_mul_f32 v[44:45], v[44:45], v[146:147]
	v_pk_mul_f32 v[40:41], v[40:41], v[150:151]
	v_pk_mul_f32 v[36:37], v[36:37], v[154:155]
	v_pk_mul_f32 v[46:47], v[46:47], v[148:149]
	v_pk_mul_f32 v[42:43], v[42:43], v[152:153]
	v_pk_mul_f32 v[38:39], v[38:39], v[156:157]
	v_pk_mul_f32 v[34:35], v[34:35], v[182:183]
	v_pk_mul_f32 v[32:33], v[32:33], v[180:181]
	v_pk_mul_f32 v[28:29], v[28:29], v[146:147]
	v_pk_mul_f32 v[24:25], v[24:25], v[150:151]
	v_pk_mul_f32 v[20:21], v[20:21], v[154:155]
	v_pk_mul_f32 v[30:31], v[30:31], v[148:149]
	v_pk_mul_f32 v[26:27], v[26:27], v[152:153]
	v_pk_mul_f32 v[22:23], v[22:23], v[156:157]
	v_pk_mul_f32 v[18:19], v[18:19], v[182:183]
	v_pk_mul_f32 v[16:17], v[16:17], v[180:181]

; __device__ __forceinline__ int otid(int wvs) { int l; asm volatile("v_mbcnt_lo_u32_b32 %0, -1, 0\n\tv_mbcnt_hi_u32_b32 %0, -1, %0" : "=v"(l)); return wvs * 64 + l; }
; #define EPI_LOOP(...) _Pragma("unroll") for(int ai=0;ai<2;++ai) _Pragma("unroll") for(int bj=0;bj<2;++bj) _Pragma("unroll") for(int m=0;m<4;++m) \
;     _Pragma("unroll") for(int n=0;n<2;++n){ const int rl=ai*HALF+ewr*64+m*16+efr, cl=bj*HALF+ewc*32+n*16+efq*4; const int R=brow+rl, Cc=bcol+cl; \
;       f32x4 v=acc[ai][bj][m][n]; __VA_ARGS__ }
; #define PUT(val) *(uint2*)(g_smem + est_off(rl_, cl)) = pack4(val)
; #define STAGED2(WBODY, SBODY) { { constexpr int AIV = 0; (void)AIV; HLOOP(0, WBODY) __syncthreads(); WLOOP(0, SBODY) } __syncthreads(); { constexpr int AIV = 1; (void)AIV; HLOOP(1, WBODY) __syncthreads(); WLOOP(1, SBODY) } }
; __device__ __forceinline__ void gemm_epi(const Job& J, f32x4 (&acc)[2][2][4][2], int brow, int bcol, int wvs) {
;     ...
;   const int te_ = otid(wvs); const int ewr = (te_ >> 8) & 1, ewc = (te_ >> 6) & 3, efr = te_ & 15, efq = (te_ >> 4) & 3;
;     ...
;   switch (mode) {
;   case E_F32: { float* C = (float*)J.C; EPI_LOOP({ v *= sc; *(f32x4*)(C + (long)R * ldc + Cc) = v; }) } return;
;   default: break;
;   }
;     ...
;   switch (mode) {
;   case E_UPACT: { u16* C = (u16*)J.C; const u16* G = (const u16*)J.aux; const float* cw = (const float*)J.aux2; const float* cb = (const float*)J.aux3; const int lg = J.flag;
;     STAGED2(({ int pos = R & ((1 << lg) - 1); const u16* gp = G + (long)R * DFF + Cc;
;         f32x4 g0 = unpack4(*(const uint2*)gp), gm = {0.f, 0.f, 0.f, 0.f}, gn = {0.f, 0.f, 0.f, 0.f};
;         if (pos > 0) gm = unpack4(*(const uint2*)(gp - DFF));
;         if (pos < (1 << lg) - 1) gn = unpack4(*(const uint2*)(gp + DFF));
;         f32x4 w0 = *(const f32x4*)(cw + Cc), w1 = *(const f32x4*)(cw + DFF + Cc), w2 = *(const f32x4*)(cw + 2 * DFF + Cc), bb = *(const f32x4*)(cb + Cc);
;         f32x4 o; _Pragma("unroll") for (int j = 0; j < 4; ++j) { float cv = gm[j] * w0[j] + g0[j] * w1[j] + gn[j] * w2[j] + bb[j]; o[j] = gelu_tanh(cv) * v[j]; }
;         PUT(o); }), ({ *(u32x4*)(C + (long)R * ldc + Cc) = LDV; })) } break;
.LBB0_516:
	v_mbcnt_lo_u32_b32 v210, -1, 0
	v_mbcnt_hi_u32_b32 v210, -1, v210
	s_mov_b64 s[6:7], -1
	v_add_u32_e32 v213, s69, v210
	v_bfe_u32 v207, v213, 8, 1
	v_bfe_u32 v208, v213, 6, 2
	v_and_b32_e32 v209, 15, v210
	v_lshrrev_b32_e32 v211, 4, v213
	v_bfe_u32 v212, v213, 4, 2
	s_mov_b64 s[52:53], 0
	s_cmp_lt_i32 s91, 5
	s_mov_b64 s[8:9], 0
	s_cbranch_scc1 .LBB0_696
	s_cmp_gt_i32 s91, 6
	s_cbranch_scc0 .LBB0_676
	s_cmp_gt_i32 s91, 8
	s_cbranch_scc0 .LBB0_654
	s_cmp_eq_u32 s91, 9
	s_mov_b64 s[8:9], -1
	s_cbranch_scc0 .LBB0_653
	v_lshlrev_b32_e32 v228, 2, v212
	v_lshl_or_b32 v229, v208, 5, v228
	v_lshl_or_b32 v230, v207, 6, v209
	v_add_u32_e32 v231, s22, v229
	v_add_u32_e32 v224, s90, v230
	v_lshlrev_b32_e32 v220, 2, v231
	v_lshlrev_b32_e32 v231, 1, v231
	s_movk_i32 s42, 0x2c00
	v_mad_u32_u24 v221, v224, s42, v231
	v_lshlrev_b32_e32 v228, 16, v207
	v_lshl_add_u32 v228, v209, 9, v228
	v_and_b32_e32 v231, 1, v212
	v_lshl_add_u32 v228, v231, 3, v228
	v_lshrrev_b32_e32 v231, 1, v212
	v_lshl_or_b32 v231, v208, 2, v231
	v_xor_b32_e32 v231, v231, v209
	v_lshl_add_u32 v222, v231, 4, v228
	v_xor_b32_e32 v231, 2, v231
	v_lshl_add_u32 v223, v231, 4, v228
	s_add_u32 s14, s46, 0xffffd400
	s_addc_u32 s15, s47, -1
	s_add_u32 s16, s46, 0x2c00
	s_addc_u32 s17, s47, 0
	s_add_u32 s18, s12, 0x5800
	s_addc_u32 s19, s13, 0
	s_add_u32 s20, s12, 0xb000
	s_addc_u32 s21, s13, 0
	s_lshl_b32 s31, 1, s95
	s_add_i32 s31, s31, -1
	s_add_i32 s84, s90, 0x80
	s_mov_b32 s96, 0x3dd2d3e7
	s_mov_b32 s97, 0x3dd2d3e7
	v_mov_b32_e32 v232, 0x40135761
	v_mov_b32_e32 v233, 0x40135761
	global_load_dwordx4 v[128:131], v220, s[12:13] offset:0
	global_load_dwordx4 v[132:135], v220, s[18:19] offset:0
	global_load_dwordx4 v[136:139], v220, s[20:21] offset:0
	global_load_dwordx4 v[140:143], v220, s[10:11] offset:0
	global_load_dwordx4 v[144:147], v220, s[12:13] offset:64
	global_load_dwordx4 v[148:151], v220, s[18:19] offset:64
	global_load_dwordx4 v[152:155], v220, s[20:21] offset:64
	global_load_dwordx4 v[156:159], v220, s[10:11] offset:64
	v_mov_b32_e32 v225, v221
	global_load_dwordx2 v[162:163], v225, s[46:47] offset:0
	global_load_dwordx2 v[164:165], v225, s[14:15] offset:0
	global_load_dwordx2 v[166:167], v225, s[16:17] offset:0
	global_load_dwordx2 v[168:169], v225, s[46:47] offset:32
	global_load_dwordx2 v[170:171], v225, s[14:15] offset:32
	global_load_dwordx2 v[172:173], v225, s[16:17] offset:32
	v_add_u32_e32 v225, 0x2c000, v221
	global_load_dwordx2 v[174:175], v225, s[46:47] offset:0
	global_load_dwordx2 v[176:177], v225, s[14:15] offset:0
	global_load_dwordx2 v[178:179], v225, s[16:17] offset:0
	global_load_dwordx2 v[180:181], v225, s[46:47] offset:32
	global_load_dwordx2 v[182:183], v225, s[14:15] offset:32
	global_load_dwordx2 v[184:185], v225, s[16:17] offset:32
	v_add_u32_e32 v225, 0x58000, v221
	global_load_dwordx2 v[186:187], v225, s[46:47] offset:0
	global_load_dwordx2 v[188:189], v225, s[14:15] offset:0
	global_load_dwordx2 v[190:191], v225, s[16:17] offset:0
	global_load_dwordx2 v[192:193], v225, s[46:47] offset:32
	global_load_dwordx2 v[194:195], v225, s[14:15] offset:32
	global_load_dwordx2 v[196:197], v225, s[16:17] offset:32
	v_add_u32_e32 v225, 0x84000, v221
	global_load_dwordx2 v[198:199], v225, s[46:47] offset:0
	global_load_dwordx2 v[200:201], v225, s[14:15] offset:0
	global_load_dwordx2 v[202:203], v225, s[16:17] offset:0
	global_load_dwordx2 v[214:215], v225, s[46:47] offset:32
	global_load_dwordx2 v[216:217], v225, s[14:15] offset:32
	global_load_dwordx2 v[218:219], v225, s[16:17] offset:32
	s_waitcnt vmcnt(0)
	v_mov_b32_e32 v228, v224
	v_and_b32_e32 v228, s31, v228
	v_cmp_ne_u32_e32 vcc, 0, v228
	s_nop 1
	v_cndmask_b32_e64 v226, 0, -1, vcc
	v_and_b32_e32 v164, v226, v164
	v_and_b32_e32 v165, v226, v165
	v_lshlrev_b32_e32 v236, 16, v164
	v_and_b32_e32 v237, 0xffff0000, v164
	v_lshlrev_b32_e32 v238, 16, v165
	v_and_b32_e32 v239, 0xffff0000, v165
	v_lshlrev_b32_e32 v240, 16, v162
	v_and_b32_e32 v241, 0xffff0000, v162
	v_lshlrev_b32_e32 v242, 16, v163
	v_and_b32_e32 v243, 0xffff0000, v163
	v_lshlrev_b32_e32 v244, 16, v166
	v_and_b32_e32 v245, 0xffff0000, v166
	v_lshlrev_b32_e32 v246, 16, v167
	v_and_b32_e32 v247, 0xffff0000, v167
	v_pk_fma_f32 v[248:249], v[236:237], v[128:129], v[140:141]
	v_pk_fma_f32 v[236:237], v[238:239], v[130:131], v[142:143]
	v_pk_fma_f32 v[248:249], v[132:133], v[240:241], v[248:249]
	v_pk_fma_f32 v[236:237], v[134:135], v[242:243], v[236:237]
	v_pk_fma_f32 v[248:249], v[244:245], v[136:137], v[248:249]
	v_pk_fma_f32 v[236:237], v[246:247], v[138:139], v[236:237]
	v_pk_mul_f32 v[250:251], v[248:249], v[248:249]
	v_pk_mul_f32 v[252:253], v[236:237], v[236:237]
	v_pk_fma_f32 v[250:251], v[250:251], s[96:97], v[232:233] op_sel_hi:[1,0,1]
	v_pk_fma_f32 v[252:253], v[252:253], s[96:97], v[232:233] op_sel_hi:[1,0,1]
	v_pk_mul_f32 v[250:251], v[248:249], v[250:251]
	v_pk_mul_f32 v[252:253], v[236:237], v[252:253]
	v_exp_f32_e32 v250, v250
	v_exp_f32_e32 v251, v251
	v_exp_f32_e32 v252, v252
	v_exp_f32_e32 v253, v253
	v_pk_add_f32 v[250:251], v[250:251], 1.0 op_sel_hi:[1,0]
	v_pk_add_f32 v[252:253], v[252:253], 1.0 op_sel_hi:[1,0]
	v_rcp_f32_e32 v250, v250
	v_rcp_f32_e32 v251, v251
	v_rcp_f32_e32 v252, v252
	v_rcp_f32_e32 v253, v253
	v_pk_fma_f32 v[250:251], v[248:249], v[250:251], v[248:249] neg_lo:[1,0,0] neg_hi:[1,0,0]
	v_pk_fma_f32 v[252:253], v[236:237], v[252:253], v[236:237] neg_lo:[1,0,0] neg_hi:[1,0,0]
	v_pk_mul_f32 v[250:251], v[124:125], v[250:251]
	v_pk_mul_f32 v[252:253], v[126:127], v[252:253]
	v_cvt_pk_bf16_f32 v248, v250, v251
	v_cvt_pk_bf16_f32 v249, v252, v253
	ds_write_b64 v222, v[248:249] offset:32768
	v_and_b32_e32 v170, v226, v170
; #define PUT(val) *(uint2*)(g_smem + est_off(rl_, cl)) = pack4(val)
; #define STAGED2(WBODY, SBODY) { { constexpr int AIV = 0; (void)AIV; HLOOP(0, WBODY) __syncthreads(); WLOOP(0, SBODY) } __syncthreads(); { constexpr int AIV = 1; (void)AIV; HLOOP(1, WBODY) __syncthreads(); WLOOP(1, SBODY) } }
; __device__ __forceinline__ void gemm_epi(const Job& J, f32x4 (&acc)[2][2][4][2], int brow, int bcol, int wvs) {
;     ...
;     STAGED2(({ int pos = R & ((1 << lg) - 1); const u16* gp = G + (long)R * DFF + Cc;
;         f32x4 g0 = unpack4(*(const uint2*)gp), gm = {0.f, 0.f, 0.f, 0.f}, gn = {0.f, 0.f, 0.f, 0.f};
;         if (pos > 0) gm = unpack4(*(const uint2*)(gp - DFF));
;         if (pos < (1 << lg) - 1) gn = unpack4(*(const uint2*)(gp + DFF));
;         f32x4 w0 = *(const f32x4*)(cw + Cc), w1 = *(const f32x4*)(cw + DFF + Cc), w2 = *(const f32x4*)(cw + 2 * DFF + Cc), bb = *(const f32x4*)(cb + Cc);
;         f32x4 o; _Pragma("unroll") for (int j = 0; j < 4; ++j) { float cv = gm[j] * w0[j] + g0[j] * w1[j] + gn[j] * w2[j] + bb[j]; o[j] = gelu_tanh(cv) * v[j]; }
;         PUT(o); }), ({ *(u32x4*)(C + (long)R * ldc + Cc) = LDV; })) } break;
	v_and_b32_e32 v171, v226, v171
	v_lshlrev_b32_e32 v236, 16, v170
	v_and_b32_e32 v237, 0xffff0000, v170
	v_lshlrev_b32_e32 v238, 16, v171
	v_and_b32_e32 v239, 0xffff0000, v171
	v_lshlrev_b32_e32 v240, 16, v168
	v_and_b32_e32 v241, 0xffff0000, v168
	v_lshlrev_b32_e32 v242, 16, v169
	v_and_b32_e32 v243, 0xffff0000, v169
	v_lshlrev_b32_e32 v244, 16, v172
	v_and_b32_e32 v245, 0xffff0000, v172
	v_lshlrev_b32_e32 v246, 16, v173
	v_and_b32_e32 v247, 0xffff0000, v173
	v_pk_fma_f32 v[248:249], v[236:237], v[144:145], v[156:157]
	v_pk_fma_f32 v[236:237], v[238:239], v[146:147], v[158:159]
	v_pk_fma_f32 v[248:249], v[148:149], v[240:241], v[248:249]
	v_pk_fma_f32 v[236:237], v[150:151], v[242:243], v[236:237]
	v_pk_fma_f32 v[248:249], v[244:245], v[152:153], v[248:249]
	v_pk_fma_f32 v[236:237], v[246:247], v[154:155], v[236:237]
	v_pk_mul_f32 v[250:251], v[248:249], v[248:249]
	v_pk_mul_f32 v[252:253], v[236:237], v[236:237]
	v_pk_fma_f32 v[250:251], v[250:251], s[96:97], v[232:233] op_sel_hi:[1,0,1]
	v_pk_fma_f32 v[252:253], v[252:253], s[96:97], v[232:233] op_sel_hi:[1,0,1]
	v_pk_mul_f32 v[250:251], v[248:249], v[250:251]
	v_pk_mul_f32 v[252:253], v[236:237], v[252:253]
	v_exp_f32_e32 v250, v250
	v_exp_f32_e32 v251, v251
	v_exp_f32_e32 v252, v252
	v_exp_f32_e32 v253, v253
	v_pk_add_f32 v[250:251], v[250:251], 1.0 op_sel_hi:[1,0]
	v_pk_add_f32 v[252:253], v[252:253], 1.0 op_sel_hi:[1,0]
	v_rcp_f32_e32 v250, v250
	v_rcp_f32_e32 v251, v251
	v_rcp_f32_e32 v252, v252
	v_rcp_f32_e32 v253, v253
	v_pk_fma_f32 v[250:251], v[248:249], v[250:251], v[248:249] neg_lo:[1,0,0] neg_hi:[1,0,0]
	v_pk_fma_f32 v[252:253], v[236:237], v[252:253], v[236:237] neg_lo:[1,0,0] neg_hi:[1,0,0]
	v_pk_mul_f32 v[250:251], v[120:121], v[250:251]
	v_pk_mul_f32 v[252:253], v[122:123], v[252:253]
	v_cvt_pk_bf16_f32 v248, v250, v251
	v_cvt_pk_bf16_f32 v249, v252, v253
	ds_write_b64 v223, v[248:249] offset:32768
	v_lshlrev_b32_e32 v236, 16, v176
	v_and_b32_e32 v237, 0xffff0000, v176
	v_lshlrev_b32_e32 v238, 16, v177
	v_and_b32_e32 v239, 0xffff0000, v177
	v_lshlrev_b32_e32 v240, 16, v174
	v_and_b32_e32 v241, 0xffff0000, v174
	v_lshlrev_b32_e32 v242, 16, v175
	v_and_b32_e32 v243, 0xffff0000, v175
	v_lshlrev_b32_e32 v244, 16, v178
	v_and_b32_e32 v245, 0xffff0000, v178
	v_lshlrev_b32_e32 v246, 16, v179
	v_and_b32_e32 v247, 0xffff0000, v179
	v_pk_fma_f32 v[248:249], v[236:237], v[128:129], v[140:141]
	v_pk_fma_f32 v[236:237], v[238:239], v[130:131], v[142:143]
	v_pk_fma_f32 v[248:249], v[132:133], v[240:241], v[248:249]
	v_pk_fma_f32 v[236:237], v[134:135], v[242:243], v[236:237]
	v_pk_fma_f32 v[248:249], v[244:245], v[136:137], v[248:249]
	v_pk_fma_f32 v[236:237], v[246:247], v[138:139], v[236:237]
	v_pk_mul_f32 v[250:251], v[248:249], v[248:249]
	v_pk_mul_f32 v[252:253], v[236:237], v[236:237]
	v_pk_fma_f32 v[250:251], v[250:251], s[96:97], v[232:233] op_sel_hi:[1,0,1]
	v_pk_fma_f32 v[252:253], v[252:253], s[96:97], v[232:233] op_sel_hi:[1,0,1]
	v_pk_mul_f32 v[250:251], v[248:249], v[250:251]
	v_pk_mul_f32 v[252:253], v[236:237], v[252:253]
	v_exp_f32_e32 v250, v250
	v_exp_f32_e32 v251, v251
	v_exp_f32_e32 v252, v252
	v_exp_f32_e32 v253, v253
	v_pk_add_f32 v[250:251], v[250:251], 1.0 op_sel_hi:[1,0]
	v_pk_add_f32 v[252:253], v[252:253], 1.0 op_sel_hi:[1,0]
	v_rcp_f32_e32 v250, v250
	v_rcp_f32_e32 v251, v251
	v_rcp_f32_e32 v252, v252
	v_rcp_f32_e32 v253, v253
	v_pk_fma_f32 v[250:251], v[248:249], v[250:251], v[248:249] neg_lo:[1,0,0] neg_hi:[1,0,0]
	v_pk_fma_f32 v[252:253], v[236:237], v[252:253], v[236:237] neg_lo:[1,0,0] neg_hi:[1,0,0]
	v_pk_mul_f32 v[250:251], v[116:117], v[250:251]
	v_pk_mul_f32 v[252:253], v[118:119], v[252:253]
	v_cvt_pk_bf16_f32 v248, v250, v251
	v_cvt_pk_bf16_f32 v249, v252, v253
	ds_write_b64 v222, v[248:249] offset:41216
	v_lshlrev_b32_e32 v236, 16, v182
	v_and_b32_e32 v237, 0xffff0000, v182
	v_lshlrev_b32_e32 v238, 16, v183
	v_and_b32_e32 v239, 0xffff0000, v183
	v_lshlrev_b32_e32 v240, 16, v180
	v_and_b32_e32 v241, 0xffff0000, v180
	v_lshlrev_b32_e32 v242, 16, v181
	v_and_b32_e32 v243, 0xffff0000, v181
	v_lshlrev_b32_e32 v244, 16, v184
	v_and_b32_e32 v245, 0xffff0000, v184
	v_lshlrev_b32_e32 v246, 16, v185
	v_and_b32_e32 v247, 0xffff0000, v185
	v_pk_fma_f32 v[248:249], v[236:237], v[144:145], v[156:157]
	v_pk_fma_f32 v[236:237], v[238:239], v[146:147], v[158:159]
	v_pk_fma_f32 v[248:249], v[148:149], v[240:241], v[248:249]
	v_pk_fma_f32 v[236:237], v[150:151], v[242:243], v[236:237]
	v_pk_fma_f32 v[248:249], v[244:245], v[152:153], v[248:249]
	v_pk_fma_f32 v[236:237], v[246:247], v[154:155], v[236:237]
	v_pk_mul_f32 v[250:251], v[248:249], v[248:249]
	v_pk_mul_f32 v[252:253], v[236:237], v[236:237]
	v_pk_fma_f32 v[250:251], v[250:251], s[96:97], v[232:233] op_sel_hi:[1,0,1]
	v_pk_fma_f32 v[252:253], v[252:253], s[96:97], v[232:233] op_sel_hi:[1,0,1]
	v_pk_mul_f32 v[250:251], v[248:249], v[250:251]
	v_pk_mul_f32 v[252:253], v[236:237], v[252:253]
	v_exp_f32_e32 v250, v250
	v_exp_f32_e32 v251, v251
	v_exp_f32_e32 v252, v252
	v_exp_f32_e32 v253, v253
	v_pk_add_f32 v[250:251], v[250:251], 1.0 op_sel_hi:[1,0]
	v_pk_add_f32 v[252:253], v[252:253], 1.0 op_sel_hi:[1,0]
	v_rcp_f32_e32 v250, v250
	v_rcp_f32_e32 v251, v251
	v_rcp_f32_e32 v252, v252
	v_rcp_f32_e32 v253, v253
	v_pk_fma_f32 v[250:251], v[248:249], v[250:251], v[248:249] neg_lo:[1,0,0] neg_hi:[1,0,0]
	v_pk_fma_f32 v[252:253], v[236:237], v[252:253], v[236:237] neg_lo:[1,0,0] neg_hi:[1,0,0]
	v_pk_mul_f32 v[250:251], v[112:113], v[250:251]
	v_pk_mul_f32 v[252:253], v[114:115], v[252:253]
	v_cvt_pk_bf16_f32 v248, v250, v251
	v_cvt_pk_bf16_f32 v249, v252, v253
	ds_write_b64 v223, v[248:249] offset:41216
; #define PUT(val) *(uint2*)(g_smem + est_off(rl_, cl)) = pack4(val)
; #define STAGED2(WBODY, SBODY) { { constexpr int AIV = 0; (void)AIV; HLOOP(0, WBODY) __syncthreads(); WLOOP(0, SBODY) } __syncthreads(); { constexpr int AIV = 1; (void)AIV; HLOOP(1, WBODY) __syncthreads(); WLOOP(1, SBODY) } }
; __device__ __forceinline__ void gemm_epi(const Job& J, f32x4 (&acc)[2][2][4][2], int brow, int bcol, int wvs) {
;     ...
;     STAGED2(({ int pos = R & ((1 << lg) - 1); const u16* gp = G + (long)R * DFF + Cc;
;         f32x4 g0 = unpack4(*(const uint2*)gp), gm = {0.f, 0.f, 0.f, 0.f}, gn = {0.f, 0.f, 0.f, 0.f};
;         if (pos > 0) gm = unpack4(*(const uint2*)(gp - DFF));
;         if (pos < (1 << lg) - 1) gn = unpack4(*(const uint2*)(gp + DFF));
;         f32x4 w0 = *(const f32x4*)(cw + Cc), w1 = *(const f32x4*)(cw + DFF + Cc), w2 = *(const f32x4*)(cw + 2 * DFF + Cc), bb = *(const f32x4*)(cb + Cc);
;         f32x4 o; _Pragma("unroll") for (int j = 0; j < 4; ++j) { float cv = gm[j] * w0[j] + g0[j] * w1[j] + gn[j] * w2[j] + bb[j]; o[j] = gelu_tanh(cv) * v[j]; }
;         PUT(o); }), ({ *(u32x4*)(C + (long)R * ldc + Cc) = LDV; })) } break;
	v_lshlrev_b32_e32 v236, 16, v188
	v_and_b32_e32 v237, 0xffff0000, v188
	v_lshlrev_b32_e32 v238, 16, v189
	v_and_b32_e32 v239, 0xffff0000, v189
	v_lshlrev_b32_e32 v240, 16, v186
	v_and_b32_e32 v241, 0xffff0000, v186
	v_lshlrev_b32_e32 v242, 16, v187
	v_and_b32_e32 v243, 0xffff0000, v187
	v_lshlrev_b32_e32 v244, 16, v190
	v_and_b32_e32 v245, 0xffff0000, v190
	v_lshlrev_b32_e32 v246, 16, v191
	v_and_b32_e32 v247, 0xffff0000, v191
	v_pk_fma_f32 v[248:249], v[236:237], v[128:129], v[140:141]
	v_pk_fma_f32 v[236:237], v[238:239], v[130:131], v[142:143]
	v_pk_fma_f32 v[248:249], v[132:133], v[240:241], v[248:249]
	v_pk_fma_f32 v[236:237], v[134:135], v[242:243], v[236:237]
	v_pk_fma_f32 v[248:249], v[244:245], v[136:137], v[248:249]
	v_pk_fma_f32 v[236:237], v[246:247], v[138:139], v[236:237]
	v_pk_mul_f32 v[250:251], v[248:249], v[248:249]
	v_pk_mul_f32 v[252:253], v[236:237], v[236:237]
	v_pk_fma_f32 v[250:251], v[250:251], s[96:97], v[232:233] op_sel_hi:[1,0,1]
	v_pk_fma_f32 v[252:253], v[252:253], s[96:97], v[232:233] op_sel_hi:[1,0,1]
	v_pk_mul_f32 v[250:251], v[248:249], v[250:251]
	v_pk_mul_f32 v[252:253], v[236:237], v[252:253]
	v_exp_f32_e32 v250, v250
	v_exp_f32_e32 v251, v251
	v_exp_f32_e32 v252, v252
	v_exp_f32_e32 v253, v253
	v_pk_add_f32 v[250:251], v[250:251], 1.0 op_sel_hi:[1,0]
	v_pk_add_f32 v[252:253], v[252:253], 1.0 op_sel_hi:[1,0]
	v_rcp_f32_e32 v250, v250
	v_rcp_f32_e32 v251, v251
	v_rcp_f32_e32 v252, v252
	v_rcp_f32_e32 v253, v253
	v_pk_fma_f32 v[250:251], v[248:249], v[250:251], v[248:249] neg_lo:[1,0,0] neg_hi:[1,0,0]
	v_pk_fma_f32 v[252:253], v[236:237], v[252:253], v[236:237] neg_lo:[1,0,0] neg_hi:[1,0,0]
	v_pk_mul_f32 v[250:251], v[108:109], v[250:251]
	v_pk_mul_f32 v[252:253], v[110:111], v[252:253]
	v_cvt_pk_bf16_f32 v248, v250, v251
	v_cvt_pk_bf16_f32 v249, v252, v253
	ds_write_b64 v222, v[248:249] offset:49152
	v_lshlrev_b32_e32 v236, 16, v194
	v_and_b32_e32 v237, 0xffff0000, v194
	v_lshlrev_b32_e32 v238, 16, v195
	v_and_b32_e32 v239, 0xffff0000, v195
	v_lshlrev_b32_e32 v240, 16, v192
	v_and_b32_e32 v241, 0xffff0000, v192
	v_lshlrev_b32_e32 v242, 16, v193
	v_and_b32_e32 v243, 0xffff0000, v193
	v_lshlrev_b32_e32 v244, 16, v196
	v_and_b32_e32 v245, 0xffff0000, v196
	v_lshlrev_b32_e32 v246, 16, v197
	v_and_b32_e32 v247, 0xffff0000, v197
	v_pk_fma_f32 v[248:249], v[236:237], v[144:145], v[156:157]
	v_pk_fma_f32 v[236:237], v[238:239], v[146:147], v[158:159]
	v_pk_fma_f32 v[248:249], v[148:149], v[240:241], v[248:249]
	v_pk_fma_f32 v[236:237], v[150:151], v[242:243], v[236:237]
	v_pk_fma_f32 v[248:249], v[244:245], v[152:153], v[248:249]
	v_pk_fma_f32 v[236:237], v[246:247], v[154:155], v[236:237]
	v_pk_mul_f32 v[250:251], v[248:249], v[248:249]
	v_pk_mul_f32 v[252:253], v[236:237], v[236:237]
	v_pk_fma_f32 v[250:251], v[250:251], s[96:97], v[232:233] op_sel_hi:[1,0,1]
	v_pk_fma_f32 v[252:253], v[252:253], s[96:97], v[232:233] op_sel_hi:[1,0,1]
	v_pk_mul_f32 v[250:251], v[248:249], v[250:251]
	v_pk_mul_f32 v[252:253], v[236:237], v[252:253]
	v_exp_f32_e32 v250, v250
	v_exp_f32_e32 v251, v251
	v_exp_f32_e32 v252, v252
	v_exp_f32_e32 v253, v253
	v_pk_add_f32 v[250:251], v[250:251], 1.0 op_sel_hi:[1,0]
	v_pk_add_f32 v[252:253], v[252:253], 1.0 op_sel_hi:[1,0]
	v_rcp_f32_e32 v250, v250
	v_rcp_f32_e32 v251, v251
	v_rcp_f32_e32 v252, v252
	v_rcp_f32_e32 v253, v253
	v_pk_fma_f32 v[250:251], v[248:249], v[250:251], v[248:249] neg_lo:[1,0,0] neg_hi:[1,0,0]
	v_pk_fma_f32 v[252:253], v[236:237], v[252:253], v[236:237] neg_lo:[1,0,0] neg_hi:[1,0,0]
	v_pk_mul_f32 v[250:251], v[104:105], v[250:251]
	v_pk_mul_f32 v[252:253], v[106:107], v[252:253]
	v_cvt_pk_bf16_f32 v248, v250, v251
	v_cvt_pk_bf16_f32 v249, v252, v253
	ds_write_b64 v223, v[248:249] offset:49152
	v_lshlrev_b32_e32 v236, 16, v200
	v_and_b32_e32 v237, 0xffff0000, v200
	v_lshlrev_b32_e32 v238, 16, v201
	v_and_b32_e32 v239, 0xffff0000, v201
	v_lshlrev_b32_e32 v240, 16, v198
	v_and_b32_e32 v241, 0xffff0000, v198
	v_lshlrev_b32_e32 v242, 16, v199
	v_and_b32_e32 v243, 0xffff0000, v199
	v_lshlrev_b32_e32 v244, 16, v202
	v_and_b32_e32 v245, 0xffff0000, v202
	v_lshlrev_b32_e32 v246, 16, v203
	v_and_b32_e32 v247, 0xffff0000, v203
	v_pk_fma_f32 v[248:249], v[236:237], v[128:129], v[140:141]
	v_pk_fma_f32 v[236:237], v[238:239], v[130:131], v[142:143]
	v_pk_fma_f32 v[248:249], v[132:133], v[240:241], v[248:249]
	v_pk_fma_f32 v[236:237], v[134:135], v[242:243], v[236:237]
	v_pk_fma_f32 v[248:249], v[244:245], v[136:137], v[248:249]
	v_pk_fma_f32 v[236:237], v[246:247], v[138:139], v[236:237]
	v_pk_mul_f32 v[250:251], v[248:249], v[248:249]
	v_pk_mul_f32 v[252:253], v[236:237], v[236:237]
	v_pk_fma_f32 v[250:251], v[250:251], s[96:97], v[232:233] op_sel_hi:[1,0,1]
	v_pk_fma_f32 v[252:253], v[252:253], s[96:97], v[232:233] op_sel_hi:[1,0,1]
	v_pk_mul_f32 v[250:251], v[248:249], v[250:251]
	v_pk_mul_f32 v[252:253], v[236:237], v[252:253]
	v_exp_f32_e32 v250, v250
	v_exp_f32_e32 v251, v251
	v_exp_f32_e32 v252, v252
	v_exp_f32_e32 v253, v253
	v_pk_add_f32 v[250:251], v[250:251], 1.0 op_sel_hi:[1,0]
	v_pk_add_f32 v[252:253], v[252:253], 1.0 op_sel_hi:[1,0]
	v_rcp_f32_e32 v250, v250
	v_rcp_f32_e32 v251, v251
	v_rcp_f32_e32 v252, v252
	v_rcp_f32_e32 v253, v253
	v_pk_fma_f32 v[250:251], v[248:249], v[250:251], v[248:249] neg_lo:[1,0,0] neg_hi:[1,0,0]
	v_pk_fma_f32 v[252:253], v[236:237], v[252:253], v[236:237] neg_lo:[1,0,0] neg_hi:[1,0,0]
	v_pk_mul_f32 v[250:251], v[100:101], v[250:251]
	v_pk_mul_f32 v[252:253], v[102:103], v[252:253]
	v_cvt_pk_bf16_f32 v248, v250, v251
	v_cvt_pk_bf16_f32 v249, v252, v253
	ds_write_b64 v222, v[248:249] offset:57600
	v_lshlrev_b32_e32 v236, 16, v216
; #define PUT(val) *(uint2*)(g_smem + est_off(rl_, cl)) = pack4(val)
; #define STAGED2(WBODY, SBODY) { { constexpr int AIV = 0; (void)AIV; HLOOP(0, WBODY) __syncthreads(); WLOOP(0, SBODY) } __syncthreads(); { constexpr int AIV = 1; (void)AIV; HLOOP(1, WBODY) __syncthreads(); WLOOP(1, SBODY) } }
; __device__ __forceinline__ void gemm_epi(const Job& J, f32x4 (&acc)[2][2][4][2], int brow, int bcol, int wvs) {
;     ...
;     STAGED2(({ int pos = R & ((1 << lg) - 1); const u16* gp = G + (long)R * DFF + Cc;
;         f32x4 g0 = unpack4(*(const uint2*)gp), gm = {0.f, 0.f, 0.f, 0.f}, gn = {0.f, 0.f, 0.f, 0.f};
;         if (pos > 0) gm = unpack4(*(const uint2*)(gp - DFF));
;         if (pos < (1 << lg) - 1) gn = unpack4(*(const uint2*)(gp + DFF));
;         f32x4 w0 = *(const f32x4*)(cw + Cc), w1 = *(const f32x4*)(cw + DFF + Cc), w2 = *(const f32x4*)(cw + 2 * DFF + Cc), bb = *(const f32x4*)(cb + Cc);
;         f32x4 o; _Pragma("unroll") for (int j = 0; j < 4; ++j) { float cv = gm[j] * w0[j] + g0[j] * w1[j] + gn[j] * w2[j] + bb[j]; o[j] = gelu_tanh(cv) * v[j]; }
;         PUT(o); }), ({ *(u32x4*)(C + (long)R * ldc + Cc) = LDV; })) } break;
	v_and_b32_e32 v237, 0xffff0000, v216
	v_lshlrev_b32_e32 v238, 16, v217
	v_and_b32_e32 v239, 0xffff0000, v217
	v_lshlrev_b32_e32 v240, 16, v214
	v_and_b32_e32 v241, 0xffff0000, v214
	v_lshlrev_b32_e32 v242, 16, v215
	v_and_b32_e32 v243, 0xffff0000, v215
	v_lshlrev_b32_e32 v244, 16, v218
	v_and_b32_e32 v245, 0xffff0000, v218
	v_lshlrev_b32_e32 v246, 16, v219
	v_and_b32_e32 v247, 0xffff0000, v219
	v_pk_fma_f32 v[248:249], v[236:237], v[144:145], v[156:157]
	v_pk_fma_f32 v[236:237], v[238:239], v[146:147], v[158:159]
	v_pk_fma_f32 v[248:249], v[148:149], v[240:241], v[248:249]
	v_pk_fma_f32 v[236:237], v[150:151], v[242:243], v[236:237]
	v_pk_fma_f32 v[248:249], v[244:245], v[152:153], v[248:249]
	v_pk_fma_f32 v[236:237], v[246:247], v[154:155], v[236:237]
	v_pk_mul_f32 v[250:251], v[248:249], v[248:249]
	v_pk_mul_f32 v[252:253], v[236:237], v[236:237]
	v_pk_fma_f32 v[250:251], v[250:251], s[96:97], v[232:233] op_sel_hi:[1,0,1]
	v_pk_fma_f32 v[252:253], v[252:253], s[96:97], v[232:233] op_sel_hi:[1,0,1]
	v_pk_mul_f32 v[250:251], v[248:249], v[250:251]
	v_pk_mul_f32 v[252:253], v[236:237], v[252:253]
	v_exp_f32_e32 v250, v250
	v_exp_f32_e32 v251, v251
	v_exp_f32_e32 v252, v252
	v_exp_f32_e32 v253, v253
	v_pk_add_f32 v[250:251], v[250:251], 1.0 op_sel_hi:[1,0]
	v_pk_add_f32 v[252:253], v[252:253], 1.0 op_sel_hi:[1,0]
	v_rcp_f32_e32 v250, v250
	v_rcp_f32_e32 v251, v251
	v_rcp_f32_e32 v252, v252
	v_rcp_f32_e32 v253, v253
	v_pk_fma_f32 v[250:251], v[248:249], v[250:251], v[248:249] neg_lo:[1,0,0] neg_hi:[1,0,0]
	v_pk_fma_f32 v[252:253], v[236:237], v[252:253], v[236:237] neg_lo:[1,0,0] neg_hi:[1,0,0]
	v_pk_mul_f32 v[250:251], v[92:93], v[250:251]
	v_pk_mul_f32 v[252:253], v[94:95], v[252:253]
	v_cvt_pk_bf16_f32 v248, v250, v251
	v_cvt_pk_bf16_f32 v249, v252, v253
	ds_write_b64 v223, v[248:249] offset:57600
	global_load_dwordx4 v[128:131], v220, s[12:13] offset:512
	global_load_dwordx4 v[132:135], v220, s[18:19] offset:512
	global_load_dwordx4 v[136:139], v220, s[20:21] offset:512
	global_load_dwordx4 v[140:143], v220, s[10:11] offset:512
	global_load_dwordx4 v[144:147], v220, s[12:13] offset:576
	global_load_dwordx4 v[148:151], v220, s[18:19] offset:576
	global_load_dwordx4 v[152:155], v220, s[20:21] offset:576
	global_load_dwordx4 v[156:159], v220, s[10:11] offset:576
	v_mov_b32_e32 v225, v221
	global_load_dwordx2 v[162:163], v225, s[46:47] offset:256
	global_load_dwordx2 v[164:165], v225, s[14:15] offset:256
	global_load_dwordx2 v[166:167], v225, s[16:17] offset:256
	global_load_dwordx2 v[168:169], v225, s[46:47] offset:288
	global_load_dwordx2 v[170:171], v225, s[14:15] offset:288
	global_load_dwordx2 v[172:173], v225, s[16:17] offset:288
	v_add_u32_e32 v225, 0x2c000, v221
	global_load_dwordx2 v[174:175], v225, s[46:47] offset:256
	global_load_dwordx2 v[176:177], v225, s[14:15] offset:256
	global_load_dwordx2 v[178:179], v225, s[16:17] offset:256
	global_load_dwordx2 v[180:181], v225, s[46:47] offset:288
	global_load_dwordx2 v[182:183], v225, s[14:15] offset:288
	global_load_dwordx2 v[184:185], v225, s[16:17] offset:288
	v_add_u32_e32 v225, 0x58000, v221
	global_load_dwordx2 v[186:187], v225, s[46:47] offset:256
	global_load_dwordx2 v[188:189], v225, s[14:15] offset:256
	global_load_dwordx2 v[190:191], v225, s[16:17] offset:256
	global_load_dwordx2 v[192:193], v225, s[46:47] offset:288
	global_load_dwordx2 v[194:195], v225, s[14:15] offset:288
	global_load_dwordx2 v[196:197], v225, s[16:17] offset:288
	v_add_u32_e32 v225, 0x84000, v221
	global_load_dwordx2 v[198:199], v225, s[46:47] offset:256
	global_load_dwordx2 v[200:201], v225, s[14:15] offset:256
	global_load_dwordx2 v[202:203], v225, s[16:17] offset:256
	global_load_dwordx2 v[214:215], v225, s[46:47] offset:288
	global_load_dwordx2 v[216:217], v225, s[14:15] offset:288
	global_load_dwordx2 v[218:219], v225, s[16:17] offset:288
	s_waitcnt vmcnt(0)
	v_mov_b32_e32 v228, v224
	v_and_b32_e32 v228, s31, v228
	v_cmp_ne_u32_e32 vcc, 0, v228
	s_nop 1
	v_cndmask_b32_e64 v226, 0, -1, vcc
	v_and_b32_e32 v164, v226, v164
	v_and_b32_e32 v165, v226, v165
	v_lshlrev_b32_e32 v236, 16, v164
	v_and_b32_e32 v237, 0xffff0000, v164
	v_lshlrev_b32_e32 v238, 16, v165
	v_and_b32_e32 v239, 0xffff0000, v165
	v_lshlrev_b32_e32 v240, 16, v162
	v_and_b32_e32 v241, 0xffff0000, v162
	v_lshlrev_b32_e32 v242, 16, v163
	v_and_b32_e32 v243, 0xffff0000, v163
	v_lshlrev_b32_e32 v244, 16, v166
	v_and_b32_e32 v245, 0xffff0000, v166
	v_lshlrev_b32_e32 v246, 16, v167
	v_and_b32_e32 v247, 0xffff0000, v167
	v_pk_fma_f32 v[248:249], v[236:237], v[128:129], v[140:141]
	v_pk_fma_f32 v[236:237], v[238:239], v[130:131], v[142:143]
	v_pk_fma_f32 v[248:249], v[132:133], v[240:241], v[248:249]
	v_pk_fma_f32 v[236:237], v[134:135], v[242:243], v[236:237]
	v_pk_fma_f32 v[248:249], v[244:245], v[136:137], v[248:249]
	v_pk_fma_f32 v[236:237], v[246:247], v[138:139], v[236:237]
	v_pk_mul_f32 v[250:251], v[248:249], v[248:249]
	v_pk_mul_f32 v[252:253], v[236:237], v[236:237]
	v_pk_fma_f32 v[250:251], v[250:251], s[96:97], v[232:233] op_sel_hi:[1,0,1]
	v_pk_fma_f32 v[252:253], v[252:253], s[96:97], v[232:233] op_sel_hi:[1,0,1]
	v_pk_mul_f32 v[250:251], v[248:249], v[250:251]
	v_pk_mul_f32 v[252:253], v[236:237], v[252:253]
	v_exp_f32_e32 v250, v250
	v_exp_f32_e32 v251, v251
	v_exp_f32_e32 v252, v252
	v_exp_f32_e32 v253, v253
	v_pk_add_f32 v[250:251], v[250:251], 1.0 op_sel_hi:[1,0]
	v_pk_add_f32 v[252:253], v[252:253], 1.0 op_sel_hi:[1,0]
	v_rcp_f32_e32 v250, v250
	v_rcp_f32_e32 v251, v251
	v_rcp_f32_e32 v252, v252
	v_rcp_f32_e32 v253, v253
	v_pk_fma_f32 v[250:251], v[248:249], v[250:251], v[248:249] neg_lo:[1,0,0] neg_hi:[1,0,0]
; #define PUT(val) *(uint2*)(g_smem + est_off(rl_, cl)) = pack4(val)
; #define STAGED2(WBODY, SBODY) { { constexpr int AIV = 0; (void)AIV; HLOOP(0, WBODY) __syncthreads(); WLOOP(0, SBODY) } __syncthreads(); { constexpr int AIV = 1; (void)AIV; HLOOP(1, WBODY) __syncthreads(); WLOOP(1, SBODY) } }
; __device__ __forceinline__ void gemm_epi(const Job& J, f32x4 (&acc)[2][2][4][2], int brow, int bcol, int wvs) {
;     ...
;     STAGED2(({ int pos = R & ((1 << lg) - 1); const u16* gp = G + (long)R * DFF + Cc;
;         f32x4 g0 = unpack4(*(const uint2*)gp), gm = {0.f, 0.f, 0.f, 0.f}, gn = {0.f, 0.f, 0.f, 0.f};
;         if (pos > 0) gm = unpack4(*(const uint2*)(gp - DFF));
;         if (pos < (1 << lg) - 1) gn = unpack4(*(const uint2*)(gp + DFF));
;         f32x4 w0 = *(const f32x4*)(cw + Cc), w1 = *(const f32x4*)(cw + DFF + Cc), w2 = *(const f32x4*)(cw + 2 * DFF + Cc), bb = *(const f32x4*)(cb + Cc);
;         f32x4 o; _Pragma("unroll") for (int j = 0; j < 4; ++j) { float cv = gm[j] * w0[j] + g0[j] * w1[j] + gn[j] * w2[j] + bb[j]; o[j] = gelu_tanh(cv) * v[j]; }
;         PUT(o); }), ({ *(u32x4*)(C + (long)R * ldc + Cc) = LDV; })) } break;
	v_pk_fma_f32 v[252:253], v[236:237], v[252:253], v[236:237] neg_lo:[1,0,0] neg_hi:[1,0,0]
	v_pk_mul_f32 v[250:251], v[96:97], v[250:251]
	v_pk_mul_f32 v[252:253], v[98:99], v[252:253]
	v_cvt_pk_bf16_f32 v248, v250, v251
	v_cvt_pk_bf16_f32 v249, v252, v253
	ds_write_b64 v222, v[248:249] offset:33024
	v_and_b32_e32 v170, v226, v170
	v_and_b32_e32 v171, v226, v171
	v_lshlrev_b32_e32 v236, 16, v170
	v_and_b32_e32 v237, 0xffff0000, v170
	v_lshlrev_b32_e32 v238, 16, v171
	v_and_b32_e32 v239, 0xffff0000, v171
	v_lshlrev_b32_e32 v240, 16, v168
	v_and_b32_e32 v241, 0xffff0000, v168
	v_lshlrev_b32_e32 v242, 16, v169
	v_and_b32_e32 v243, 0xffff0000, v169
	v_lshlrev_b32_e32 v244, 16, v172
	v_and_b32_e32 v245, 0xffff0000, v172
	v_lshlrev_b32_e32 v246, 16, v173
	v_and_b32_e32 v247, 0xffff0000, v173
	v_pk_fma_f32 v[248:249], v[236:237], v[144:145], v[156:157]
	v_pk_fma_f32 v[236:237], v[238:239], v[146:147], v[158:159]
	v_pk_fma_f32 v[248:249], v[148:149], v[240:241], v[248:249]
	v_pk_fma_f32 v[236:237], v[150:151], v[242:243], v[236:237]
	v_pk_fma_f32 v[248:249], v[244:245], v[152:153], v[248:249]
	v_pk_fma_f32 v[236:237], v[246:247], v[154:155], v[236:237]
	v_pk_mul_f32 v[250:251], v[248:249], v[248:249]
	v_pk_mul_f32 v[252:253], v[236:237], v[236:237]
	v_pk_fma_f32 v[250:251], v[250:251], s[96:97], v[232:233] op_sel_hi:[1,0,1]
	v_pk_fma_f32 v[252:253], v[252:253], s[96:97], v[232:233] op_sel_hi:[1,0,1]
	v_pk_mul_f32 v[250:251], v[248:249], v[250:251]
	v_pk_mul_f32 v[252:253], v[236:237], v[252:253]
	v_exp_f32_e32 v250, v250
	v_exp_f32_e32 v251, v251
	v_exp_f32_e32 v252, v252
	v_exp_f32_e32 v253, v253
	v_pk_add_f32 v[250:251], v[250:251], 1.0 op_sel_hi:[1,0]
	v_pk_add_f32 v[252:253], v[252:253], 1.0 op_sel_hi:[1,0]
	v_rcp_f32_e32 v250, v250
	v_rcp_f32_e32 v251, v251
	v_rcp_f32_e32 v252, v252
	v_rcp_f32_e32 v253, v253
	v_pk_fma_f32 v[250:251], v[248:249], v[250:251], v[248:249] neg_lo:[1,0,0] neg_hi:[1,0,0]
	v_pk_fma_f32 v[252:253], v[236:237], v[252:253], v[236:237] neg_lo:[1,0,0] neg_hi:[1,0,0]
	v_pk_mul_f32 v[250:251], v[88:89], v[250:251]
	v_pk_mul_f32 v[252:253], v[90:91], v[252:253]
	v_cvt_pk_bf16_f32 v248, v250, v251
	v_cvt_pk_bf16_f32 v249, v252, v253
	ds_write_b64 v223, v[248:249] offset:33024
	v_lshlrev_b32_e32 v236, 16, v176
	v_and_b32_e32 v237, 0xffff0000, v176
	v_lshlrev_b32_e32 v238, 16, v177
	v_and_b32_e32 v239, 0xffff0000, v177
	v_lshlrev_b32_e32 v240, 16, v174
	v_and_b32_e32 v241, 0xffff0000, v174
	v_lshlrev_b32_e32 v242, 16, v175
	v_and_b32_e32 v243, 0xffff0000, v175
	v_lshlrev_b32_e32 v244, 16, v178
	v_and_b32_e32 v245, 0xffff0000, v178
	v_lshlrev_b32_e32 v246, 16, v179
	v_and_b32_e32 v247, 0xffff0000, v179
	v_pk_fma_f32 v[248:249], v[236:237], v[128:129], v[140:141]
	v_pk_fma_f32 v[236:237], v[238:239], v[130:131], v[142:143]
	v_pk_fma_f32 v[248:249], v[132:133], v[240:241], v[248:249]
	v_pk_fma_f32 v[236:237], v[134:135], v[242:243], v[236:237]
	v_pk_fma_f32 v[248:249], v[244:245], v[136:137], v[248:249]
	v_pk_fma_f32 v[236:237], v[246:247], v[138:139], v[236:237]
	v_pk_mul_f32 v[250:251], v[248:249], v[248:249]
	v_pk_mul_f32 v[252:253], v[236:237], v[236:237]
	v_pk_fma_f32 v[250:251], v[250:251], s[96:97], v[232:233] op_sel_hi:[1,0,1]
	v_pk_fma_f32 v[252:253], v[252:253], s[96:97], v[232:233] op_sel_hi:[1,0,1]
	v_pk_mul_f32 v[250:251], v[248:249], v[250:251]
	v_pk_mul_f32 v[252:253], v[236:237], v[252:253]
	v_exp_f32_e32 v250, v250
	v_exp_f32_e32 v251, v251
	v_exp_f32_e32 v252, v252
	v_exp_f32_e32 v253, v253
	v_pk_add_f32 v[250:251], v[250:251], 1.0 op_sel_hi:[1,0]
	v_pk_add_f32 v[252:253], v[252:253], 1.0 op_sel_hi:[1,0]
	v_rcp_f32_e32 v250, v250
	v_rcp_f32_e32 v251, v251
	v_rcp_f32_e32 v252, v252
	v_rcp_f32_e32 v253, v253
	v_pk_fma_f32 v[250:251], v[248:249], v[250:251], v[248:249] neg_lo:[1,0,0] neg_hi:[1,0,0]
	v_pk_fma_f32 v[252:253], v[236:237], v[252:253], v[236:237] neg_lo:[1,0,0] neg_hi:[1,0,0]
	v_pk_mul_f32 v[250:251], v[84:85], v[250:251]
	v_pk_mul_f32 v[252:253], v[86:87], v[252:253]
	v_cvt_pk_bf16_f32 v248, v250, v251
	v_cvt_pk_bf16_f32 v249, v252, v253
	ds_write_b64 v222, v[248:249] offset:40960
	v_lshlrev_b32_e32 v236, 16, v182
	v_and_b32_e32 v237, 0xffff0000, v182
	v_lshlrev_b32_e32 v238, 16, v183
	v_and_b32_e32 v239, 0xffff0000, v183
	v_lshlrev_b32_e32 v240, 16, v180
	v_and_b32_e32 v241, 0xffff0000, v180
	v_lshlrev_b32_e32 v242, 16, v181
	v_and_b32_e32 v243, 0xffff0000, v181
	v_lshlrev_b32_e32 v244, 16, v184
	v_and_b32_e32 v245, 0xffff0000, v184
	v_lshlrev_b32_e32 v246, 16, v185
	v_and_b32_e32 v247, 0xffff0000, v185
	v_pk_fma_f32 v[248:249], v[236:237], v[144:145], v[156:157]
	v_pk_fma_f32 v[236:237], v[238:239], v[146:147], v[158:159]
	v_pk_fma_f32 v[248:249], v[148:149], v[240:241], v[248:249]
	v_pk_fma_f32 v[236:237], v[150:151], v[242:243], v[236:237]
	v_pk_fma_f32 v[248:249], v[244:245], v[152:153], v[248:249]
	v_pk_fma_f32 v[236:237], v[246:247], v[154:155], v[236:237]
	v_pk_mul_f32 v[250:251], v[248:249], v[248:249]
	v_pk_mul_f32 v[252:253], v[236:237], v[236:237]
	v_pk_fma_f32 v[250:251], v[250:251], s[96:97], v[232:233] op_sel_hi:[1,0,1]
	v_pk_fma_f32 v[252:253], v[252:253], s[96:97], v[232:233] op_sel_hi:[1,0,1]
	v_pk_mul_f32 v[250:251], v[248:249], v[250:251]
	v_pk_mul_f32 v[252:253], v[236:237], v[252:253]
	v_exp_f32_e32 v250, v250
	v_exp_f32_e32 v251, v251
	v_exp_f32_e32 v252, v252
	v_exp_f32_e32 v253, v253
	v_pk_add_f32 v[250:251], v[250:251], 1.0 op_sel_hi:[1,0]
	v_pk_add_f32 v[252:253], v[252:253], 1.0 op_sel_hi:[1,0]
	v_rcp_f32_e32 v250, v250
	v_rcp_f32_e32 v251, v251
	v_rcp_f32_e32 v252, v252
	v_rcp_f32_e32 v253, v253
	v_pk_fma_f32 v[250:251], v[248:249], v[250:251], v[248:249] neg_lo:[1,0,0] neg_hi:[1,0,0]
; #define PUT(val) *(uint2*)(g_smem + est_off(rl_, cl)) = pack4(val)
; #define STAGED2(WBODY, SBODY) { { constexpr int AIV = 0; (void)AIV; HLOOP(0, WBODY) __syncthreads(); WLOOP(0, SBODY) } __syncthreads(); { constexpr int AIV = 1; (void)AIV; HLOOP(1, WBODY) __syncthreads(); WLOOP(1, SBODY) } }
; __device__ __forceinline__ void gemm_epi(const Job& J, f32x4 (&acc)[2][2][4][2], int brow, int bcol, int wvs) {
;     ...
;     STAGED2(({ int pos = R & ((1 << lg) - 1); const u16* gp = G + (long)R * DFF + Cc;
;         f32x4 g0 = unpack4(*(const uint2*)gp), gm = {0.f, 0.f, 0.f, 0.f}, gn = {0.f, 0.f, 0.f, 0.f};
;         if (pos > 0) gm = unpack4(*(const uint2*)(gp - DFF));
;         if (pos < (1 << lg) - 1) gn = unpack4(*(const uint2*)(gp + DFF));
;         f32x4 w0 = *(const f32x4*)(cw + Cc), w1 = *(const f32x4*)(cw + DFF + Cc), w2 = *(const f32x4*)(cw + 2 * DFF + Cc), bb = *(const f32x4*)(cb + Cc);
;         f32x4 o; _Pragma("unroll") for (int j = 0; j < 4; ++j) { float cv = gm[j] * w0[j] + g0[j] * w1[j] + gn[j] * w2[j] + bb[j]; o[j] = gelu_tanh(cv) * v[j]; }
;         PUT(o); }), ({ *(u32x4*)(C + (long)R * ldc + Cc) = LDV; })) } break;
	v_pk_fma_f32 v[252:253], v[236:237], v[252:253], v[236:237] neg_lo:[1,0,0] neg_hi:[1,0,0]
	v_pk_mul_f32 v[250:251], v[80:81], v[250:251]
	v_pk_mul_f32 v[252:253], v[82:83], v[252:253]
	v_cvt_pk_bf16_f32 v248, v250, v251
	v_cvt_pk_bf16_f32 v249, v252, v253
	ds_write_b64 v223, v[248:249] offset:40960
	v_lshlrev_b32_e32 v236, 16, v188
	v_and_b32_e32 v237, 0xffff0000, v188
	v_lshlrev_b32_e32 v238, 16, v189
	v_and_b32_e32 v239, 0xffff0000, v189
	v_lshlrev_b32_e32 v240, 16, v186
	v_and_b32_e32 v241, 0xffff0000, v186
	v_lshlrev_b32_e32 v242, 16, v187
	v_and_b32_e32 v243, 0xffff0000, v187
	v_lshlrev_b32_e32 v244, 16, v190
	v_and_b32_e32 v245, 0xffff0000, v190
	v_lshlrev_b32_e32 v246, 16, v191
	v_and_b32_e32 v247, 0xffff0000, v191
	v_pk_fma_f32 v[248:249], v[236:237], v[128:129], v[140:141]
	v_pk_fma_f32 v[236:237], v[238:239], v[130:131], v[142:143]
	v_pk_fma_f32 v[248:249], v[132:133], v[240:241], v[248:249]
	v_pk_fma_f32 v[236:237], v[134:135], v[242:243], v[236:237]
	v_pk_fma_f32 v[248:249], v[244:245], v[136:137], v[248:249]
	v_pk_fma_f32 v[236:237], v[246:247], v[138:139], v[236:237]
	v_pk_mul_f32 v[250:251], v[248:249], v[248:249]
	v_pk_mul_f32 v[252:253], v[236:237], v[236:237]
	v_pk_fma_f32 v[250:251], v[250:251], s[96:97], v[232:233] op_sel_hi:[1,0,1]
	v_pk_fma_f32 v[252:253], v[252:253], s[96:97], v[232:233] op_sel_hi:[1,0,1]
	v_pk_mul_f32 v[250:251], v[248:249], v[250:251]
	v_pk_mul_f32 v[252:253], v[236:237], v[252:253]
	v_exp_f32_e32 v250, v250
	v_exp_f32_e32 v251, v251
	v_exp_f32_e32 v252, v252
	v_exp_f32_e32 v253, v253
	v_pk_add_f32 v[250:251], v[250:251], 1.0 op_sel_hi:[1,0]
	v_pk_add_f32 v[252:253], v[252:253], 1.0 op_sel_hi:[1,0]
	v_rcp_f32_e32 v250, v250
	v_rcp_f32_e32 v251, v251
	v_rcp_f32_e32 v252, v252
	v_rcp_f32_e32 v253, v253
	v_pk_fma_f32 v[250:251], v[248:249], v[250:251], v[248:249] neg_lo:[1,0,0] neg_hi:[1,0,0]
	v_pk_fma_f32 v[252:253], v[236:237], v[252:253], v[236:237] neg_lo:[1,0,0] neg_hi:[1,0,0]
	v_pk_mul_f32 v[250:251], v[76:77], v[250:251]
	v_pk_mul_f32 v[252:253], v[78:79], v[252:253]
	v_cvt_pk_bf16_f32 v248, v250, v251
	v_cvt_pk_bf16_f32 v249, v252, v253
	ds_write_b64 v222, v[248:249] offset:49408
	v_lshlrev_b32_e32 v236, 16, v194
	v_and_b32_e32 v237, 0xffff0000, v194
	v_lshlrev_b32_e32 v238, 16, v195
	v_and_b32_e32 v239, 0xffff0000, v195
	v_lshlrev_b32_e32 v240, 16, v192
	v_and_b32_e32 v241, 0xffff0000, v192
	v_lshlrev_b32_e32 v242, 16, v193
	v_and_b32_e32 v243, 0xffff0000, v193
	v_lshlrev_b32_e32 v244, 16, v196
	v_and_b32_e32 v245, 0xffff0000, v196
	v_lshlrev_b32_e32 v246, 16, v197
	v_and_b32_e32 v247, 0xffff0000, v197
	v_pk_fma_f32 v[248:249], v[236:237], v[144:145], v[156:157]
	v_pk_fma_f32 v[236:237], v[238:239], v[146:147], v[158:159]
	v_pk_fma_f32 v[248:249], v[148:149], v[240:241], v[248:249]
	v_pk_fma_f32 v[236:237], v[150:151], v[242:243], v[236:237]
	v_pk_fma_f32 v[248:249], v[244:245], v[152:153], v[248:249]
	v_pk_fma_f32 v[236:237], v[246:247], v[154:155], v[236:237]
	v_pk_mul_f32 v[250:251], v[248:249], v[248:249]
	v_pk_mul_f32 v[252:253], v[236:237], v[236:237]
	v_pk_fma_f32 v[250:251], v[250:251], s[96:97], v[232:233] op_sel_hi:[1,0,1]
	v_pk_fma_f32 v[252:253], v[252:253], s[96:97], v[232:233] op_sel_hi:[1,0,1]
	v_pk_mul_f32 v[250:251], v[248:249], v[250:251]
	v_pk_mul_f32 v[252:253], v[236:237], v[252:253]
	v_exp_f32_e32 v250, v250
	v_exp_f32_e32 v251, v251
	v_exp_f32_e32 v252, v252
	v_exp_f32_e32 v253, v253
	v_pk_add_f32 v[250:251], v[250:251], 1.0 op_sel_hi:[1,0]
	v_pk_add_f32 v[252:253], v[252:253], 1.0 op_sel_hi:[1,0]
	v_rcp_f32_e32 v250, v250
	v_rcp_f32_e32 v251, v251
	v_rcp_f32_e32 v252, v252
	v_rcp_f32_e32 v253, v253
	v_pk_fma_f32 v[250:251], v[248:249], v[250:251], v[248:249] neg_lo:[1,0,0] neg_hi:[1,0,0]
	v_pk_fma_f32 v[252:253], v[236:237], v[252:253], v[236:237] neg_lo:[1,0,0] neg_hi:[1,0,0]
	v_pk_mul_f32 v[250:251], v[72:73], v[250:251]
	v_pk_mul_f32 v[252:253], v[74:75], v[252:253]
	v_cvt_pk_bf16_f32 v248, v250, v251
	v_cvt_pk_bf16_f32 v249, v252, v253
	ds_write_b64 v223, v[248:249] offset:49408
	v_lshlrev_b32_e32 v236, 16, v200
	v_and_b32_e32 v237, 0xffff0000, v200
	v_lshlrev_b32_e32 v238, 16, v201
	v_and_b32_e32 v239, 0xffff0000, v201
	v_lshlrev_b32_e32 v240, 16, v198
	v_and_b32_e32 v241, 0xffff0000, v198
	v_lshlrev_b32_e32 v242, 16, v199
	v_and_b32_e32 v243, 0xffff0000, v199
	v_lshlrev_b32_e32 v244, 16, v202
	v_and_b32_e32 v245, 0xffff0000, v202
	v_lshlrev_b32_e32 v246, 16, v203
	v_and_b32_e32 v247, 0xffff0000, v203
	v_pk_fma_f32 v[248:249], v[236:237], v[128:129], v[140:141]
	v_pk_fma_f32 v[236:237], v[238:239], v[130:131], v[142:143]
	v_pk_fma_f32 v[248:249], v[132:133], v[240:241], v[248:249]
	v_pk_fma_f32 v[236:237], v[134:135], v[242:243], v[236:237]
	v_pk_fma_f32 v[248:249], v[244:245], v[136:137], v[248:249]
	v_pk_fma_f32 v[236:237], v[246:247], v[138:139], v[236:237]
	v_pk_mul_f32 v[250:251], v[248:249], v[248:249]
	v_pk_mul_f32 v[252:253], v[236:237], v[236:237]
	v_pk_fma_f32 v[250:251], v[250:251], s[96:97], v[232:233] op_sel_hi:[1,0,1]
	v_pk_fma_f32 v[252:253], v[252:253], s[96:97], v[232:233] op_sel_hi:[1,0,1]
	v_pk_mul_f32 v[250:251], v[248:249], v[250:251]
	v_pk_mul_f32 v[252:253], v[236:237], v[252:253]
	v_exp_f32_e32 v250, v250
	v_exp_f32_e32 v251, v251
	v_exp_f32_e32 v252, v252
	v_exp_f32_e32 v253, v253
	v_pk_add_f32 v[250:251], v[250:251], 1.0 op_sel_hi:[1,0]
	v_pk_add_f32 v[252:253], v[252:253], 1.0 op_sel_hi:[1,0]
	v_rcp_f32_e32 v250, v250
	v_rcp_f32_e32 v251, v251
	v_rcp_f32_e32 v252, v252
	v_rcp_f32_e32 v253, v253
	v_pk_fma_f32 v[250:251], v[248:249], v[250:251], v[248:249] neg_lo:[1,0,0] neg_hi:[1,0,0]
	v_pk_fma_f32 v[252:253], v[236:237], v[252:253], v[236:237] neg_lo:[1,0,0] neg_hi:[1,0,0]
; #define PUT(val) *(uint2*)(g_smem + est_off(rl_, cl)) = pack4(val)
; #define STAGED2(WBODY, SBODY) { { constexpr int AIV = 0; (void)AIV; HLOOP(0, WBODY) __syncthreads(); WLOOP(0, SBODY) } __syncthreads(); { constexpr int AIV = 1; (void)AIV; HLOOP(1, WBODY) __syncthreads(); WLOOP(1, SBODY) } }
; __device__ __forceinline__ void gemm_epi(const Job& J, f32x4 (&acc)[2][2][4][2], int brow, int bcol, int wvs) {
;     ...
;   switch (mode) {
;   case E_UPACT: { u16* C = (u16*)J.C; const u16* G = (const u16*)J.aux; const float* cw = (const float*)J.aux2; const float* cb = (const float*)J.aux3; const int lg = J.flag;
;     STAGED2(({ int pos = R & ((1 << lg) - 1); const u16* gp = G + (long)R * DFF + Cc;
;         f32x4 g0 = unpack4(*(const uint2*)gp), gm = {0.f, 0.f, 0.f, 0.f}, gn = {0.f, 0.f, 0.f, 0.f};
;         if (pos > 0) gm = unpack4(*(const uint2*)(gp - DFF));
;         if (pos < (1 << lg) - 1) gn = unpack4(*(const uint2*)(gp + DFF));
;         f32x4 w0 = *(const f32x4*)(cw + Cc), w1 = *(const f32x4*)(cw + DFF + Cc), w2 = *(const f32x4*)(cw + 2 * DFF + Cc), bb = *(const f32x4*)(cb + Cc);
;         f32x4 o; _Pragma("unroll") for (int j = 0; j < 4; ++j) { float cv = gm[j] * w0[j] + g0[j] * w1[j] + gn[j] * w2[j] + bb[j]; o[j] = gelu_tanh(cv) * v[j]; }
;         PUT(o); }), ({ *(u32x4*)(C + (long)R * ldc + Cc) = LDV; })) } break;
	v_pk_mul_f32 v[250:251], v[68:69], v[250:251]
	v_pk_mul_f32 v[252:253], v[70:71], v[252:253]
	v_cvt_pk_bf16_f32 v248, v250, v251
	v_cvt_pk_bf16_f32 v249, v252, v253
	ds_write_b64 v222, v[248:249] offset:57344
	v_lshlrev_b32_e32 v236, 16, v216
	v_and_b32_e32 v237, 0xffff0000, v216
	v_lshlrev_b32_e32 v238, 16, v217
	v_and_b32_e32 v239, 0xffff0000, v217
	v_lshlrev_b32_e32 v240, 16, v214
	v_and_b32_e32 v241, 0xffff0000, v214
	v_lshlrev_b32_e32 v242, 16, v215
	v_and_b32_e32 v243, 0xffff0000, v215
	v_lshlrev_b32_e32 v244, 16, v218
	v_and_b32_e32 v245, 0xffff0000, v218
	v_lshlrev_b32_e32 v246, 16, v219
	v_and_b32_e32 v247, 0xffff0000, v219
	v_pk_fma_f32 v[248:249], v[236:237], v[144:145], v[156:157]
	v_pk_fma_f32 v[236:237], v[238:239], v[146:147], v[158:159]
	v_pk_fma_f32 v[248:249], v[148:149], v[240:241], v[248:249]
	v_pk_fma_f32 v[236:237], v[150:151], v[242:243], v[236:237]
	v_pk_fma_f32 v[248:249], v[244:245], v[152:153], v[248:249]
	v_pk_fma_f32 v[236:237], v[246:247], v[154:155], v[236:237]
	v_pk_mul_f32 v[250:251], v[248:249], v[248:249]
	v_pk_mul_f32 v[252:253], v[236:237], v[236:237]
	v_pk_fma_f32 v[250:251], v[250:251], s[96:97], v[232:233] op_sel_hi:[1,0,1]
	v_pk_fma_f32 v[252:253], v[252:253], s[96:97], v[232:233] op_sel_hi:[1,0,1]
	v_pk_mul_f32 v[250:251], v[248:249], v[250:251]
	v_pk_mul_f32 v[252:253], v[236:237], v[252:253]
	v_exp_f32_e32 v250, v250
	v_exp_f32_e32 v251, v251
	v_exp_f32_e32 v252, v252
	v_exp_f32_e32 v253, v253
	v_pk_add_f32 v[250:251], v[250:251], 1.0 op_sel_hi:[1,0]
	v_pk_add_f32 v[252:253], v[252:253], 1.0 op_sel_hi:[1,0]
	v_rcp_f32_e32 v250, v250
	v_rcp_f32_e32 v251, v251
	v_rcp_f32_e32 v252, v252
	v_rcp_f32_e32 v253, v253
	v_pk_fma_f32 v[250:251], v[248:249], v[250:251], v[248:249] neg_lo:[1,0,0] neg_hi:[1,0,0]
	v_pk_fma_f32 v[252:253], v[236:237], v[252:253], v[236:237] neg_lo:[1,0,0] neg_hi:[1,0,0]
	v_pk_mul_f32 v[250:251], v[64:65], v[250:251]
	v_pk_mul_f32 v[252:253], v[66:67], v[252:253]
	v_cvt_pk_bf16_f32 v248, v250, v251
	v_cvt_pk_bf16_f32 v249, v252, v253
	ds_write_b64 v223, v[248:249] offset:57344
	s_waitcnt lgkmcnt(0)
	s_barrier
	v_add_u32_e32 v99, s69, v210
	v_lshrrev_b32_e32 v99, 5, v99
	v_and_b32_e32 v98, 31, v210
	v_xor_b32_e32 v96, v98, v99
	v_lshlrev_b32_e32 v96, 4, v96
	v_xor_b32_e32 v97, 0x100, v96
	v_lshl_add_u32 v96, v99, 9, v96
	v_lshl_add_u32 v97, v99, 9, v97
	v_mul_u32_u24_e32 v99, s4, v99
	v_lshlrev_b32_e32 v98, 4, v98
	v_lshl_add_u32 v98, v99, 1, v98
	s_mul_i32 s6, s90, s4
	s_add_i32 s6, s6, s22
	s_lshl_b32 s6, s6, 1
	s_add_u32 s6, s26, s6
	s_addc_u32 s7, s27, 0
	s_lshl_b32 s8, s4, 5
	ds_read_b128 v[64:67], v96 offset:32768
	ds_read_b128 v[68:71], v97 offset:40960
	ds_read_b128 v[72:75], v96 offset:49152
	ds_read_b128 v[76:79], v97 offset:57344
	v_add_u32_e32 v96, 0x10000, v96
	v_add_u32_e32 v97, 0x10000, v97
	ds_read_b128 v[80:83], v96 offset:32768
	ds_read_b128 v[84:87], v97 offset:40960
	ds_read_b128 v[88:91], v96 offset:49152
	ds_read_b128 v[92:95], v97 offset:57344
	s_waitcnt lgkmcnt(7)
	global_store_dwordx4 v98, v[64:67], s[6:7]
	s_add_u32 s6, s6, s8
	s_addc_u32 s7, s7, 0
	s_waitcnt lgkmcnt(6)
	global_store_dwordx4 v98, v[68:71], s[6:7]
	s_add_u32 s6, s6, s8
	s_addc_u32 s7, s7, 0
	s_waitcnt lgkmcnt(5)
	global_store_dwordx4 v98, v[72:75], s[6:7]
	s_add_u32 s6, s6, s8
	s_addc_u32 s7, s7, 0
	s_waitcnt lgkmcnt(4)
	global_store_dwordx4 v98, v[76:79], s[6:7]
	s_add_u32 s6, s6, s8
	s_addc_u32 s7, s7, 0
	s_waitcnt lgkmcnt(3)
	global_store_dwordx4 v98, v[80:83], s[6:7]
	s_add_u32 s6, s6, s8
	s_addc_u32 s7, s7, 0
	s_waitcnt lgkmcnt(2)
	global_store_dwordx4 v98, v[84:87], s[6:7]
	s_add_u32 s6, s6, s8
	s_addc_u32 s7, s7, 0
	s_waitcnt lgkmcnt(1)
	global_store_dwordx4 v98, v[88:91], s[6:7]
	s_add_u32 s6, s6, s8
	s_addc_u32 s7, s7, 0
	s_waitcnt lgkmcnt(0)
	global_store_dwordx4 v98, v[92:95], s[6:7]
	s_waitcnt lgkmcnt(0)
	s_barrier
	global_load_dwordx4 v[128:131], v220, s[12:13] offset:0
	global_load_dwordx4 v[132:135], v220, s[18:19] offset:0
	global_load_dwordx4 v[136:139], v220, s[20:21] offset:0
	global_load_dwordx4 v[140:143], v220, s[10:11] offset:0
	global_load_dwordx4 v[144:147], v220, s[12:13] offset:64
	global_load_dwordx4 v[148:151], v220, s[18:19] offset:64
	global_load_dwordx4 v[152:155], v220, s[20:21] offset:64
	global_load_dwordx4 v[156:159], v220, s[10:11] offset:64
	v_add_u32_e32 v225, 0x160000, v221
	global_load_dwordx2 v[162:163], v225, s[46:47] offset:0
	global_load_dwordx2 v[164:165], v225, s[14:15] offset:0
	global_load_dwordx2 v[166:167], v225, s[16:17] offset:0
	global_load_dwordx2 v[168:169], v225, s[46:47] offset:32
	global_load_dwordx2 v[170:171], v225, s[14:15] offset:32
	global_load_dwordx2 v[172:173], v225, s[16:17] offset:32
	v_add_u32_e32 v225, 0x18c000, v221
	global_load_dwordx2 v[174:175], v225, s[46:47] offset:0
	global_load_dwordx2 v[176:177], v225, s[14:15] offset:0
	global_load_dwordx2 v[178:179], v225, s[16:17] offset:0
	global_load_dwordx2 v[180:181], v225, s[46:47] offset:32
	global_load_dwordx2 v[182:183], v225, s[14:15] offset:32
	global_load_dwordx2 v[184:185], v225, s[16:17] offset:32
	v_add_u32_e32 v225, 0x1b8000, v221
	global_load_dwordx2 v[186:187], v225, s[46:47] offset:0
	global_load_dwordx2 v[188:189], v225, s[14:15] offset:0
	global_load_dwordx2 v[190:191], v225, s[16:17] offset:0
	global_load_dwordx2 v[192:193], v225, s[46:47] offset:32
	global_load_dwordx2 v[194:195], v225, s[14:15] offset:32
	global_load_dwordx2 v[196:197], v225, s[16:17] offset:32
	v_add_u32_e32 v225, 0x1e4000, v221
	global_load_dwordx2 v[198:199], v225, s[46:47] offset:0
	global_load_dwordx2 v[200:201], v225, s[14:15] offset:0
	global_load_dwordx2 v[202:203], v225, s[16:17] offset:0
	global_load_dwordx2 v[214:215], v225, s[46:47] offset:32
	global_load_dwordx2 v[216:217], v225, s[14:15] offset:32
	global_load_dwordx2 v[218:219], v225, s[16:17] offset:32
	s_waitcnt vmcnt(0)
; #define PUT(val) *(uint2*)(g_smem + est_off(rl_, cl)) = pack4(val)
; #define STAGED2(WBODY, SBODY) { { constexpr int AIV = 0; (void)AIV; HLOOP(0, WBODY) __syncthreads(); WLOOP(0, SBODY) } __syncthreads(); { constexpr int AIV = 1; (void)AIV; HLOOP(1, WBODY) __syncthreads(); WLOOP(1, SBODY) } }
; __device__ __forceinline__ void gemm_epi(const Job& J, f32x4 (&acc)[2][2][4][2], int brow, int bcol, int wvs) {
;     ...
;     STAGED2(({ int pos = R & ((1 << lg) - 1); const u16* gp = G + (long)R * DFF + Cc;
;         f32x4 g0 = unpack4(*(const uint2*)gp), gm = {0.f, 0.f, 0.f, 0.f}, gn = {0.f, 0.f, 0.f, 0.f};
;         if (pos > 0) gm = unpack4(*(const uint2*)(gp - DFF));
;         if (pos < (1 << lg) - 1) gn = unpack4(*(const uint2*)(gp + DFF));
;         f32x4 w0 = *(const f32x4*)(cw + Cc), w1 = *(const f32x4*)(cw + DFF + Cc), w2 = *(const f32x4*)(cw + 2 * DFF + Cc), bb = *(const f32x4*)(cb + Cc);
;         f32x4 o; _Pragma("unroll") for (int j = 0; j < 4; ++j) { float cv = gm[j] * w0[j] + g0[j] * w1[j] + gn[j] * w2[j] + bb[j]; o[j] = gelu_tanh(cv) * v[j]; }
;         PUT(o); }), ({ *(u32x4*)(C + (long)R * ldc + Cc) = LDV; })) } break;
	v_lshlrev_b32_e32 v236, 16, v164
	v_and_b32_e32 v237, 0xffff0000, v164
	v_lshlrev_b32_e32 v238, 16, v165
	v_and_b32_e32 v239, 0xffff0000, v165
	v_lshlrev_b32_e32 v240, 16, v162
	v_and_b32_e32 v241, 0xffff0000, v162
	v_lshlrev_b32_e32 v242, 16, v163
	v_and_b32_e32 v243, 0xffff0000, v163
	v_lshlrev_b32_e32 v244, 16, v166
	v_and_b32_e32 v245, 0xffff0000, v166
	v_lshlrev_b32_e32 v246, 16, v167
	v_and_b32_e32 v247, 0xffff0000, v167
	v_pk_fma_f32 v[248:249], v[236:237], v[128:129], v[140:141]
	v_pk_fma_f32 v[236:237], v[238:239], v[130:131], v[142:143]
	v_pk_fma_f32 v[248:249], v[132:133], v[240:241], v[248:249]
	v_pk_fma_f32 v[236:237], v[134:135], v[242:243], v[236:237]
	v_pk_fma_f32 v[248:249], v[244:245], v[136:137], v[248:249]
	v_pk_fma_f32 v[236:237], v[246:247], v[138:139], v[236:237]
	v_pk_mul_f32 v[250:251], v[248:249], v[248:249]
	v_pk_mul_f32 v[252:253], v[236:237], v[236:237]
	v_pk_fma_f32 v[250:251], v[250:251], s[96:97], v[232:233] op_sel_hi:[1,0,1]
	v_pk_fma_f32 v[252:253], v[252:253], s[96:97], v[232:233] op_sel_hi:[1,0,1]
	v_pk_mul_f32 v[250:251], v[248:249], v[250:251]
	v_pk_mul_f32 v[252:253], v[236:237], v[252:253]
	v_exp_f32_e32 v250, v250
	v_exp_f32_e32 v251, v251
	v_exp_f32_e32 v252, v252
	v_exp_f32_e32 v253, v253
	v_pk_add_f32 v[250:251], v[250:251], 1.0 op_sel_hi:[1,0]
	v_pk_add_f32 v[252:253], v[252:253], 1.0 op_sel_hi:[1,0]
	v_rcp_f32_e32 v250, v250
	v_rcp_f32_e32 v251, v251
	v_rcp_f32_e32 v252, v252
	v_rcp_f32_e32 v253, v253
	v_pk_fma_f32 v[250:251], v[248:249], v[250:251], v[248:249] neg_lo:[1,0,0] neg_hi:[1,0,0]
	v_pk_fma_f32 v[252:253], v[236:237], v[252:253], v[236:237] neg_lo:[1,0,0] neg_hi:[1,0,0]
	v_pk_mul_f32 v[250:251], v[60:61], v[250:251]
	v_pk_mul_f32 v[252:253], v[62:63], v[252:253]
	v_cvt_pk_bf16_f32 v248, v250, v251
	v_cvt_pk_bf16_f32 v249, v252, v253
	ds_write_b64 v222, v[248:249] offset:32768
	v_lshlrev_b32_e32 v236, 16, v170
	v_and_b32_e32 v237, 0xffff0000, v170
	v_lshlrev_b32_e32 v238, 16, v171
	v_and_b32_e32 v239, 0xffff0000, v171
	v_lshlrev_b32_e32 v240, 16, v168
	v_and_b32_e32 v241, 0xffff0000, v168
	v_lshlrev_b32_e32 v242, 16, v169
	v_and_b32_e32 v243, 0xffff0000, v169
	v_lshlrev_b32_e32 v244, 16, v172
	v_and_b32_e32 v245, 0xffff0000, v172
	v_lshlrev_b32_e32 v246, 16, v173
	v_and_b32_e32 v247, 0xffff0000, v173
	v_pk_fma_f32 v[248:249], v[236:237], v[144:145], v[156:157]
	v_pk_fma_f32 v[236:237], v[238:239], v[146:147], v[158:159]
	v_pk_fma_f32 v[248:249], v[148:149], v[240:241], v[248:249]
	v_pk_fma_f32 v[236:237], v[150:151], v[242:243], v[236:237]
	v_pk_fma_f32 v[248:249], v[244:245], v[152:153], v[248:249]
	v_pk_fma_f32 v[236:237], v[246:247], v[154:155], v[236:237]
	v_pk_mul_f32 v[250:251], v[248:249], v[248:249]
	v_pk_mul_f32 v[252:253], v[236:237], v[236:237]
	v_pk_fma_f32 v[250:251], v[250:251], s[96:97], v[232:233] op_sel_hi:[1,0,1]
	v_pk_fma_f32 v[252:253], v[252:253], s[96:97], v[232:233] op_sel_hi:[1,0,1]
	v_pk_mul_f32 v[250:251], v[248:249], v[250:251]
	v_pk_mul_f32 v[252:253], v[236:237], v[252:253]
	v_exp_f32_e32 v250, v250
	v_exp_f32_e32 v251, v251
	v_exp_f32_e32 v252, v252
	v_exp_f32_e32 v253, v253
	v_pk_add_f32 v[250:251], v[250:251], 1.0 op_sel_hi:[1,0]
	v_pk_add_f32 v[252:253], v[252:253], 1.0 op_sel_hi:[1,0]
	v_rcp_f32_e32 v250, v250
	v_rcp_f32_e32 v251, v251
	v_rcp_f32_e32 v252, v252
	v_rcp_f32_e32 v253, v253
	v_pk_fma_f32 v[250:251], v[248:249], v[250:251], v[248:249] neg_lo:[1,0,0] neg_hi:[1,0,0]
	v_pk_fma_f32 v[252:253], v[236:237], v[252:253], v[236:237] neg_lo:[1,0,0] neg_hi:[1,0,0]
	v_pk_mul_f32 v[250:251], v[56:57], v[250:251]
	v_pk_mul_f32 v[252:253], v[58:59], v[252:253]
	v_cvt_pk_bf16_f32 v248, v250, v251
	v_cvt_pk_bf16_f32 v249, v252, v253
	ds_write_b64 v223, v[248:249] offset:32768
	v_lshlrev_b32_e32 v236, 16, v176
	v_and_b32_e32 v237, 0xffff0000, v176
	v_lshlrev_b32_e32 v238, 16, v177
	v_and_b32_e32 v239, 0xffff0000, v177
	v_lshlrev_b32_e32 v240, 16, v174
	v_and_b32_e32 v241, 0xffff0000, v174
	v_lshlrev_b32_e32 v242, 16, v175
	v_and_b32_e32 v243, 0xffff0000, v175
	v_lshlrev_b32_e32 v244, 16, v178
	v_and_b32_e32 v245, 0xffff0000, v178
	v_lshlrev_b32_e32 v246, 16, v179
	v_and_b32_e32 v247, 0xffff0000, v179
	v_pk_fma_f32 v[248:249], v[236:237], v[128:129], v[140:141]
	v_pk_fma_f32 v[236:237], v[238:239], v[130:131], v[142:143]
	v_pk_fma_f32 v[248:249], v[132:133], v[240:241], v[248:249]
	v_pk_fma_f32 v[236:237], v[134:135], v[242:243], v[236:237]
	v_pk_fma_f32 v[248:249], v[244:245], v[136:137], v[248:249]
	v_pk_fma_f32 v[236:237], v[246:247], v[138:139], v[236:237]
	v_pk_mul_f32 v[250:251], v[248:249], v[248:249]
	v_pk_mul_f32 v[252:253], v[236:237], v[236:237]
	v_pk_fma_f32 v[250:251], v[250:251], s[96:97], v[232:233] op_sel_hi:[1,0,1]
	v_pk_fma_f32 v[252:253], v[252:253], s[96:97], v[232:233] op_sel_hi:[1,0,1]
	v_pk_mul_f32 v[250:251], v[248:249], v[250:251]
	v_pk_mul_f32 v[252:253], v[236:237], v[252:253]
	v_exp_f32_e32 v250, v250
	v_exp_f32_e32 v251, v251
	v_exp_f32_e32 v252, v252
	v_exp_f32_e32 v253, v253
	v_pk_add_f32 v[250:251], v[250:251], 1.0 op_sel_hi:[1,0]
	v_pk_add_f32 v[252:253], v[252:253], 1.0 op_sel_hi:[1,0]
	v_rcp_f32_e32 v250, v250
	v_rcp_f32_e32 v251, v251
	v_rcp_f32_e32 v252, v252
	v_rcp_f32_e32 v253, v253
	v_pk_fma_f32 v[250:251], v[248:249], v[250:251], v[248:249] neg_lo:[1,0,0] neg_hi:[1,0,0]
	v_pk_fma_f32 v[252:253], v[236:237], v[252:253], v[236:237] neg_lo:[1,0,0] neg_hi:[1,0,0]
	v_pk_mul_f32 v[250:251], v[52:53], v[250:251]
	v_pk_mul_f32 v[252:253], v[54:55], v[252:253]
	v_cvt_pk_bf16_f32 v248, v250, v251
	v_cvt_pk_bf16_f32 v249, v252, v253
	ds_write_b64 v222, v[248:249] offset:41216
	v_lshlrev_b32_e32 v236, 16, v182
; #define PUT(val) *(uint2*)(g_smem + est_off(rl_, cl)) = pack4(val)
; #define STAGED2(WBODY, SBODY) { { constexpr int AIV = 0; (void)AIV; HLOOP(0, WBODY) __syncthreads(); WLOOP(0, SBODY) } __syncthreads(); { constexpr int AIV = 1; (void)AIV; HLOOP(1, WBODY) __syncthreads(); WLOOP(1, SBODY) } }
; __device__ __forceinline__ void gemm_epi(const Job& J, f32x4 (&acc)[2][2][4][2], int brow, int bcol, int wvs) {
;     ...
;     STAGED2(({ int pos = R & ((1 << lg) - 1); const u16* gp = G + (long)R * DFF + Cc;
;         f32x4 g0 = unpack4(*(const uint2*)gp), gm = {0.f, 0.f, 0.f, 0.f}, gn = {0.f, 0.f, 0.f, 0.f};
;         if (pos > 0) gm = unpack4(*(const uint2*)(gp - DFF));
;         if (pos < (1 << lg) - 1) gn = unpack4(*(const uint2*)(gp + DFF));
;         f32x4 w0 = *(const f32x4*)(cw + Cc), w1 = *(const f32x4*)(cw + DFF + Cc), w2 = *(const f32x4*)(cw + 2 * DFF + Cc), bb = *(const f32x4*)(cb + Cc);
;         f32x4 o; _Pragma("unroll") for (int j = 0; j < 4; ++j) { float cv = gm[j] * w0[j] + g0[j] * w1[j] + gn[j] * w2[j] + bb[j]; o[j] = gelu_tanh(cv) * v[j]; }
;         PUT(o); }), ({ *(u32x4*)(C + (long)R * ldc + Cc) = LDV; })) } break;
	v_and_b32_e32 v237, 0xffff0000, v182
	v_lshlrev_b32_e32 v238, 16, v183
	v_and_b32_e32 v239, 0xffff0000, v183
	v_lshlrev_b32_e32 v240, 16, v180
	v_and_b32_e32 v241, 0xffff0000, v180
	v_lshlrev_b32_e32 v242, 16, v181
	v_and_b32_e32 v243, 0xffff0000, v181
	v_lshlrev_b32_e32 v244, 16, v184
	v_and_b32_e32 v245, 0xffff0000, v184
	v_lshlrev_b32_e32 v246, 16, v185
	v_and_b32_e32 v247, 0xffff0000, v185
	v_pk_fma_f32 v[248:249], v[236:237], v[144:145], v[156:157]
	v_pk_fma_f32 v[236:237], v[238:239], v[146:147], v[158:159]
	v_pk_fma_f32 v[248:249], v[148:149], v[240:241], v[248:249]
	v_pk_fma_f32 v[236:237], v[150:151], v[242:243], v[236:237]
	v_pk_fma_f32 v[248:249], v[244:245], v[152:153], v[248:249]
	v_pk_fma_f32 v[236:237], v[246:247], v[154:155], v[236:237]
	v_pk_mul_f32 v[250:251], v[248:249], v[248:249]
	v_pk_mul_f32 v[252:253], v[236:237], v[236:237]
	v_pk_fma_f32 v[250:251], v[250:251], s[96:97], v[232:233] op_sel_hi:[1,0,1]
	v_pk_fma_f32 v[252:253], v[252:253], s[96:97], v[232:233] op_sel_hi:[1,0,1]
	v_pk_mul_f32 v[250:251], v[248:249], v[250:251]
	v_pk_mul_f32 v[252:253], v[236:237], v[252:253]
	v_exp_f32_e32 v250, v250
	v_exp_f32_e32 v251, v251
	v_exp_f32_e32 v252, v252
	v_exp_f32_e32 v253, v253
	v_pk_add_f32 v[250:251], v[250:251], 1.0 op_sel_hi:[1,0]
	v_pk_add_f32 v[252:253], v[252:253], 1.0 op_sel_hi:[1,0]
	v_rcp_f32_e32 v250, v250
	v_rcp_f32_e32 v251, v251
	v_rcp_f32_e32 v252, v252
	v_rcp_f32_e32 v253, v253
	v_pk_fma_f32 v[250:251], v[248:249], v[250:251], v[248:249] neg_lo:[1,0,0] neg_hi:[1,0,0]
	v_pk_fma_f32 v[252:253], v[236:237], v[252:253], v[236:237] neg_lo:[1,0,0] neg_hi:[1,0,0]
	v_pk_mul_f32 v[250:251], v[48:49], v[250:251]
	v_pk_mul_f32 v[252:253], v[50:51], v[252:253]
	v_cvt_pk_bf16_f32 v248, v250, v251
	v_cvt_pk_bf16_f32 v249, v252, v253
	ds_write_b64 v223, v[248:249] offset:41216
	v_lshlrev_b32_e32 v236, 16, v188
	v_and_b32_e32 v237, 0xffff0000, v188
	v_lshlrev_b32_e32 v238, 16, v189
	v_and_b32_e32 v239, 0xffff0000, v189
	v_lshlrev_b32_e32 v240, 16, v186
	v_and_b32_e32 v241, 0xffff0000, v186
	v_lshlrev_b32_e32 v242, 16, v187
	v_and_b32_e32 v243, 0xffff0000, v187
	v_lshlrev_b32_e32 v244, 16, v190
	v_and_b32_e32 v245, 0xffff0000, v190
	v_lshlrev_b32_e32 v246, 16, v191
	v_and_b32_e32 v247, 0xffff0000, v191
	v_pk_fma_f32 v[248:249], v[236:237], v[128:129], v[140:141]
	v_pk_fma_f32 v[236:237], v[238:239], v[130:131], v[142:143]
	v_pk_fma_f32 v[248:249], v[132:133], v[240:241], v[248:249]
	v_pk_fma_f32 v[236:237], v[134:135], v[242:243], v[236:237]
	v_pk_fma_f32 v[248:249], v[244:245], v[136:137], v[248:249]
	v_pk_fma_f32 v[236:237], v[246:247], v[138:139], v[236:237]
	v_pk_mul_f32 v[250:251], v[248:249], v[248:249]
	v_pk_mul_f32 v[252:253], v[236:237], v[236:237]
	v_pk_fma_f32 v[250:251], v[250:251], s[96:97], v[232:233] op_sel_hi:[1,0,1]
	v_pk_fma_f32 v[252:253], v[252:253], s[96:97], v[232:233] op_sel_hi:[1,0,1]
	v_pk_mul_f32 v[250:251], v[248:249], v[250:251]
	v_pk_mul_f32 v[252:253], v[236:237], v[252:253]
	v_exp_f32_e32 v250, v250
	v_exp_f32_e32 v251, v251
	v_exp_f32_e32 v252, v252
	v_exp_f32_e32 v253, v253
	v_pk_add_f32 v[250:251], v[250:251], 1.0 op_sel_hi:[1,0]
	v_pk_add_f32 v[252:253], v[252:253], 1.0 op_sel_hi:[1,0]
	v_rcp_f32_e32 v250, v250
	v_rcp_f32_e32 v251, v251
	v_rcp_f32_e32 v252, v252
	v_rcp_f32_e32 v253, v253
	v_pk_fma_f32 v[250:251], v[248:249], v[250:251], v[248:249] neg_lo:[1,0,0] neg_hi:[1,0,0]
	v_pk_fma_f32 v[252:253], v[236:237], v[252:253], v[236:237] neg_lo:[1,0,0] neg_hi:[1,0,0]
	v_pk_mul_f32 v[250:251], v[44:45], v[250:251]
	v_pk_mul_f32 v[252:253], v[46:47], v[252:253]
	v_cvt_pk_bf16_f32 v248, v250, v251
	v_cvt_pk_bf16_f32 v249, v252, v253
	ds_write_b64 v222, v[248:249] offset:49152
	v_lshlrev_b32_e32 v236, 16, v194
	v_and_b32_e32 v237, 0xffff0000, v194
	v_lshlrev_b32_e32 v238, 16, v195
	v_and_b32_e32 v239, 0xffff0000, v195
	v_lshlrev_b32_e32 v240, 16, v192
	v_and_b32_e32 v241, 0xffff0000, v192
	v_lshlrev_b32_e32 v242, 16, v193
	v_and_b32_e32 v243, 0xffff0000, v193
	v_lshlrev_b32_e32 v244, 16, v196
	v_and_b32_e32 v245, 0xffff0000, v196
	v_lshlrev_b32_e32 v246, 16, v197
	v_and_b32_e32 v247, 0xffff0000, v197
	v_pk_fma_f32 v[248:249], v[236:237], v[144:145], v[156:157]
	v_pk_fma_f32 v[236:237], v[238:239], v[146:147], v[158:159]
	v_pk_fma_f32 v[248:249], v[148:149], v[240:241], v[248:249]
	v_pk_fma_f32 v[236:237], v[150:151], v[242:243], v[236:237]
	v_pk_fma_f32 v[248:249], v[244:245], v[152:153], v[248:249]
	v_pk_fma_f32 v[236:237], v[246:247], v[154:155], v[236:237]
	v_pk_mul_f32 v[250:251], v[248:249], v[248:249]
	v_pk_mul_f32 v[252:253], v[236:237], v[236:237]
	v_pk_fma_f32 v[250:251], v[250:251], s[96:97], v[232:233] op_sel_hi:[1,0,1]
	v_pk_fma_f32 v[252:253], v[252:253], s[96:97], v[232:233] op_sel_hi:[1,0,1]
	v_pk_mul_f32 v[250:251], v[248:249], v[250:251]
	v_pk_mul_f32 v[252:253], v[236:237], v[252:253]
	v_exp_f32_e32 v250, v250
	v_exp_f32_e32 v251, v251
	v_exp_f32_e32 v252, v252
	v_exp_f32_e32 v253, v253
	v_pk_add_f32 v[250:251], v[250:251], 1.0 op_sel_hi:[1,0]
	v_pk_add_f32 v[252:253], v[252:253], 1.0 op_sel_hi:[1,0]
	v_rcp_f32_e32 v250, v250
	v_rcp_f32_e32 v251, v251
	v_rcp_f32_e32 v252, v252
	v_rcp_f32_e32 v253, v253
	v_pk_fma_f32 v[250:251], v[248:249], v[250:251], v[248:249] neg_lo:[1,0,0] neg_hi:[1,0,0]
	v_pk_fma_f32 v[252:253], v[236:237], v[252:253], v[236:237] neg_lo:[1,0,0] neg_hi:[1,0,0]
	v_pk_mul_f32 v[250:251], v[40:41], v[250:251]
	v_pk_mul_f32 v[252:253], v[42:43], v[252:253]
	v_cvt_pk_bf16_f32 v248, v250, v251
	v_cvt_pk_bf16_f32 v249, v252, v253
	ds_write_b64 v223, v[248:249] offset:49152
	v_add_u32_e32 v228, 176, v224
	v_and_b32_e32 v228, s31, v228
	v_cmp_ne_u32_e32 vcc, s31, v228
; #define PUT(val) *(uint2*)(g_smem + est_off(rl_, cl)) = pack4(val)
; #define STAGED2(WBODY, SBODY) { { constexpr int AIV = 0; (void)AIV; HLOOP(0, WBODY) __syncthreads(); WLOOP(0, SBODY) } __syncthreads(); { constexpr int AIV = 1; (void)AIV; HLOOP(1, WBODY) __syncthreads(); WLOOP(1, SBODY) } }
; __device__ __forceinline__ void gemm_epi(const Job& J, f32x4 (&acc)[2][2][4][2], int brow, int bcol, int wvs) {
;     ...
;     STAGED2(({ int pos = R & ((1 << lg) - 1); const u16* gp = G + (long)R * DFF + Cc;
;         f32x4 g0 = unpack4(*(const uint2*)gp), gm = {0.f, 0.f, 0.f, 0.f}, gn = {0.f, 0.f, 0.f, 0.f};
;         if (pos > 0) gm = unpack4(*(const uint2*)(gp - DFF));
;         if (pos < (1 << lg) - 1) gn = unpack4(*(const uint2*)(gp + DFF));
;         f32x4 w0 = *(const f32x4*)(cw + Cc), w1 = *(const f32x4*)(cw + DFF + Cc), w2 = *(const f32x4*)(cw + 2 * DFF + Cc), bb = *(const f32x4*)(cb + Cc);
;         f32x4 o; _Pragma("unroll") for (int j = 0; j < 4; ++j) { float cv = gm[j] * w0[j] + g0[j] * w1[j] + gn[j] * w2[j] + bb[j]; o[j] = gelu_tanh(cv) * v[j]; }
;         PUT(o); }), ({ *(u32x4*)(C + (long)R * ldc + Cc) = LDV; })) } break;
	s_nop 1
	v_cndmask_b32_e64 v226, 0, -1, vcc
	v_and_b32_e32 v202, v226, v202
	v_and_b32_e32 v203, v226, v203
	v_lshlrev_b32_e32 v236, 16, v200
	v_and_b32_e32 v237, 0xffff0000, v200
	v_lshlrev_b32_e32 v238, 16, v201
	v_and_b32_e32 v239, 0xffff0000, v201
	v_lshlrev_b32_e32 v240, 16, v198
	v_and_b32_e32 v241, 0xffff0000, v198
	v_lshlrev_b32_e32 v242, 16, v199
	v_and_b32_e32 v243, 0xffff0000, v199
	v_lshlrev_b32_e32 v244, 16, v202
	v_and_b32_e32 v245, 0xffff0000, v202
	v_lshlrev_b32_e32 v246, 16, v203
	v_and_b32_e32 v247, 0xffff0000, v203
	v_pk_fma_f32 v[248:249], v[236:237], v[128:129], v[140:141]
	v_pk_fma_f32 v[236:237], v[238:239], v[130:131], v[142:143]
	v_pk_fma_f32 v[248:249], v[132:133], v[240:241], v[248:249]
	v_pk_fma_f32 v[236:237], v[134:135], v[242:243], v[236:237]
	v_pk_fma_f32 v[248:249], v[244:245], v[136:137], v[248:249]
	v_pk_fma_f32 v[236:237], v[246:247], v[138:139], v[236:237]
	v_pk_mul_f32 v[250:251], v[248:249], v[248:249]
	v_pk_mul_f32 v[252:253], v[236:237], v[236:237]
	v_pk_fma_f32 v[250:251], v[250:251], s[96:97], v[232:233] op_sel_hi:[1,0,1]
	v_pk_fma_f32 v[252:253], v[252:253], s[96:97], v[232:233] op_sel_hi:[1,0,1]
	v_pk_mul_f32 v[250:251], v[248:249], v[250:251]
	v_pk_mul_f32 v[252:253], v[236:237], v[252:253]
	v_exp_f32_e32 v250, v250
	v_exp_f32_e32 v251, v251
	v_exp_f32_e32 v252, v252
	v_exp_f32_e32 v253, v253
	v_pk_add_f32 v[250:251], v[250:251], 1.0 op_sel_hi:[1,0]
	v_pk_add_f32 v[252:253], v[252:253], 1.0 op_sel_hi:[1,0]
	v_rcp_f32_e32 v250, v250
	v_rcp_f32_e32 v251, v251
	v_rcp_f32_e32 v252, v252
	v_rcp_f32_e32 v253, v253
	v_pk_fma_f32 v[250:251], v[248:249], v[250:251], v[248:249] neg_lo:[1,0,0] neg_hi:[1,0,0]
	v_pk_fma_f32 v[252:253], v[236:237], v[252:253], v[236:237] neg_lo:[1,0,0] neg_hi:[1,0,0]
	v_pk_mul_f32 v[250:251], v[36:37], v[250:251]
	v_pk_mul_f32 v[252:253], v[38:39], v[252:253]
	v_cvt_pk_bf16_f32 v248, v250, v251
	v_cvt_pk_bf16_f32 v249, v252, v253
	ds_write_b64 v222, v[248:249] offset:57600
	v_and_b32_e32 v218, v226, v218
	v_and_b32_e32 v219, v226, v219
	v_lshlrev_b32_e32 v236, 16, v216
	v_and_b32_e32 v237, 0xffff0000, v216
	v_lshlrev_b32_e32 v238, 16, v217
	v_and_b32_e32 v239, 0xffff0000, v217
	v_lshlrev_b32_e32 v240, 16, v214
	v_and_b32_e32 v241, 0xffff0000, v214
	v_lshlrev_b32_e32 v242, 16, v215
	v_and_b32_e32 v243, 0xffff0000, v215
	v_lshlrev_b32_e32 v244, 16, v218
	v_and_b32_e32 v245, 0xffff0000, v218
	v_lshlrev_b32_e32 v246, 16, v219
	v_and_b32_e32 v247, 0xffff0000, v219
	v_pk_fma_f32 v[248:249], v[236:237], v[144:145], v[156:157]
	v_pk_fma_f32 v[236:237], v[238:239], v[146:147], v[158:159]
	v_pk_fma_f32 v[248:249], v[148:149], v[240:241], v[248:249]
	v_pk_fma_f32 v[236:237], v[150:151], v[242:243], v[236:237]
	v_pk_fma_f32 v[248:249], v[244:245], v[152:153], v[248:249]
	v_pk_fma_f32 v[236:237], v[246:247], v[154:155], v[236:237]
	v_pk_mul_f32 v[250:251], v[248:249], v[248:249]
	v_pk_mul_f32 v[252:253], v[236:237], v[236:237]
	v_pk_fma_f32 v[250:251], v[250:251], s[96:97], v[232:233] op_sel_hi:[1,0,1]
	v_pk_fma_f32 v[252:253], v[252:253], s[96:97], v[232:233] op_sel_hi:[1,0,1]
	v_pk_mul_f32 v[250:251], v[248:249], v[250:251]
	v_pk_mul_f32 v[252:253], v[236:237], v[252:253]
	v_exp_f32_e32 v250, v250
	v_exp_f32_e32 v251, v251
	v_exp_f32_e32 v252, v252
	v_exp_f32_e32 v253, v253
	v_pk_add_f32 v[250:251], v[250:251], 1.0 op_sel_hi:[1,0]
	v_pk_add_f32 v[252:253], v[252:253], 1.0 op_sel_hi:[1,0]
	v_rcp_f32_e32 v250, v250
	v_rcp_f32_e32 v251, v251
	v_rcp_f32_e32 v252, v252
	v_rcp_f32_e32 v253, v253
	v_pk_fma_f32 v[250:251], v[248:249], v[250:251], v[248:249] neg_lo:[1,0,0] neg_hi:[1,0,0]
	v_pk_fma_f32 v[252:253], v[236:237], v[252:253], v[236:237] neg_lo:[1,0,0] neg_hi:[1,0,0]
	v_pk_mul_f32 v[250:251], v[32:33], v[250:251]
	v_pk_mul_f32 v[252:253], v[34:35], v[252:253]
	v_cvt_pk_bf16_f32 v248, v250, v251
	v_cvt_pk_bf16_f32 v249, v252, v253
	ds_write_b64 v223, v[248:249] offset:57600
	global_load_dwordx4 v[128:131], v220, s[12:13] offset:512
	global_load_dwordx4 v[132:135], v220, s[18:19] offset:512
	global_load_dwordx4 v[136:139], v220, s[20:21] offset:512
	global_load_dwordx4 v[140:143], v220, s[10:11] offset:512
	global_load_dwordx4 v[144:147], v220, s[12:13] offset:576
	global_load_dwordx4 v[148:151], v220, s[18:19] offset:576
	global_load_dwordx4 v[152:155], v220, s[20:21] offset:576
	global_load_dwordx4 v[156:159], v220, s[10:11] offset:576
	v_add_u32_e32 v225, 0x160000, v221
	global_load_dwordx2 v[162:163], v225, s[46:47] offset:256
	global_load_dwordx2 v[164:165], v225, s[14:15] offset:256
	global_load_dwordx2 v[166:167], v225, s[16:17] offset:256
	global_load_dwordx2 v[168:169], v225, s[46:47] offset:288
	global_load_dwordx2 v[170:171], v225, s[14:15] offset:288
	global_load_dwordx2 v[172:173], v225, s[16:17] offset:288
	v_add_u32_e32 v225, 0x18c000, v221
	global_load_dwordx2 v[174:175], v225, s[46:47] offset:256
	global_load_dwordx2 v[176:177], v225, s[14:15] offset:256
	global_load_dwordx2 v[178:179], v225, s[16:17] offset:256
	global_load_dwordx2 v[180:181], v225, s[46:47] offset:288
	global_load_dwordx2 v[182:183], v225, s[14:15] offset:288
	global_load_dwordx2 v[184:185], v225, s[16:17] offset:288
	v_add_u32_e32 v225, 0x1b8000, v221
	global_load_dwordx2 v[186:187], v225, s[46:47] offset:256
	global_load_dwordx2 v[188:189], v225, s[14:15] offset:256
	global_load_dwordx2 v[190:191], v225, s[16:17] offset:256
	global_load_dwordx2 v[192:193], v225, s[46:47] offset:288
	global_load_dwordx2 v[194:195], v225, s[14:15] offset:288
	global_load_dwordx2 v[196:197], v225, s[16:17] offset:288
	v_add_u32_e32 v225, 0x1e4000, v221
	global_load_dwordx2 v[198:199], v225, s[46:47] offset:256
	global_load_dwordx2 v[200:201], v225, s[14:15] offset:256
	global_load_dwordx2 v[202:203], v225, s[16:17] offset:256
	global_load_dwordx2 v[214:215], v225, s[46:47] offset:288
	global_load_dwordx2 v[216:217], v225, s[14:15] offset:288
	global_load_dwordx2 v[218:219], v225, s[16:17] offset:288
	s_waitcnt vmcnt(0)
; #define PUT(val) *(uint2*)(g_smem + est_off(rl_, cl)) = pack4(val)
; #define STAGED2(WBODY, SBODY) { { constexpr int AIV = 0; (void)AIV; HLOOP(0, WBODY) __syncthreads(); WLOOP(0, SBODY) } __syncthreads(); { constexpr int AIV = 1; (void)AIV; HLOOP(1, WBODY) __syncthreads(); WLOOP(1, SBODY) } }
; __device__ __forceinline__ void gemm_epi(const Job& J, f32x4 (&acc)[2][2][4][2], int brow, int bcol, int wvs) {
;     ...
;     STAGED2(({ int pos = R & ((1 << lg) - 1); const u16* gp = G + (long)R * DFF + Cc;
;         f32x4 g0 = unpack4(*(const uint2*)gp), gm = {0.f, 0.f, 0.f, 0.f}, gn = {0.f, 0.f, 0.f, 0.f};
;         if (pos > 0) gm = unpack4(*(const uint2*)(gp - DFF));
;         if (pos < (1 << lg) - 1) gn = unpack4(*(const uint2*)(gp + DFF));
;         f32x4 w0 = *(const f32x4*)(cw + Cc), w1 = *(const f32x4*)(cw + DFF + Cc), w2 = *(const f32x4*)(cw + 2 * DFF + Cc), bb = *(const f32x4*)(cb + Cc);
;         f32x4 o; _Pragma("unroll") for (int j = 0; j < 4; ++j) { float cv = gm[j] * w0[j] + g0[j] * w1[j] + gn[j] * w2[j] + bb[j]; o[j] = gelu_tanh(cv) * v[j]; }
;         PUT(o); }), ({ *(u32x4*)(C + (long)R * ldc + Cc) = LDV; })) } break;
	v_lshlrev_b32_e32 v236, 16, v164
	v_and_b32_e32 v237, 0xffff0000, v164
	v_lshlrev_b32_e32 v238, 16, v165
	v_and_b32_e32 v239, 0xffff0000, v165
	v_lshlrev_b32_e32 v240, 16, v162
	v_and_b32_e32 v241, 0xffff0000, v162
	v_lshlrev_b32_e32 v242, 16, v163
	v_and_b32_e32 v243, 0xffff0000, v163
	v_lshlrev_b32_e32 v244, 16, v166
	v_and_b32_e32 v245, 0xffff0000, v166
	v_lshlrev_b32_e32 v246, 16, v167
	v_and_b32_e32 v247, 0xffff0000, v167
	v_pk_fma_f32 v[248:249], v[236:237], v[128:129], v[140:141]
	v_pk_fma_f32 v[236:237], v[238:239], v[130:131], v[142:143]
	v_pk_fma_f32 v[248:249], v[132:133], v[240:241], v[248:249]
	v_pk_fma_f32 v[236:237], v[134:135], v[242:243], v[236:237]
	v_pk_fma_f32 v[248:249], v[244:245], v[136:137], v[248:249]
	v_pk_fma_f32 v[236:237], v[246:247], v[138:139], v[236:237]
	v_pk_mul_f32 v[250:251], v[248:249], v[248:249]
	v_pk_mul_f32 v[252:253], v[236:237], v[236:237]
	v_pk_fma_f32 v[250:251], v[250:251], s[96:97], v[232:233] op_sel_hi:[1,0,1]
	v_pk_fma_f32 v[252:253], v[252:253], s[96:97], v[232:233] op_sel_hi:[1,0,1]
	v_pk_mul_f32 v[250:251], v[248:249], v[250:251]
	v_pk_mul_f32 v[252:253], v[236:237], v[252:253]
	v_exp_f32_e32 v250, v250
	v_exp_f32_e32 v251, v251
	v_exp_f32_e32 v252, v252
	v_exp_f32_e32 v253, v253
	v_pk_add_f32 v[250:251], v[250:251], 1.0 op_sel_hi:[1,0]
	v_pk_add_f32 v[252:253], v[252:253], 1.0 op_sel_hi:[1,0]
	v_rcp_f32_e32 v250, v250
	v_rcp_f32_e32 v251, v251
	v_rcp_f32_e32 v252, v252
	v_rcp_f32_e32 v253, v253
	v_pk_fma_f32 v[250:251], v[248:249], v[250:251], v[248:249] neg_lo:[1,0,0] neg_hi:[1,0,0]
	v_pk_fma_f32 v[252:253], v[236:237], v[252:253], v[236:237] neg_lo:[1,0,0] neg_hi:[1,0,0]
	v_pk_mul_f32 v[250:251], v[28:29], v[250:251]
	v_pk_mul_f32 v[252:253], v[30:31], v[252:253]
	v_cvt_pk_bf16_f32 v248, v250, v251
	v_cvt_pk_bf16_f32 v249, v252, v253
	ds_write_b64 v222, v[248:249] offset:33024
	v_lshlrev_b32_e32 v236, 16, v170
	v_and_b32_e32 v237, 0xffff0000, v170
	v_lshlrev_b32_e32 v238, 16, v171
	v_and_b32_e32 v239, 0xffff0000, v171
	v_lshlrev_b32_e32 v240, 16, v168
	v_and_b32_e32 v241, 0xffff0000, v168
	v_lshlrev_b32_e32 v242, 16, v169
	v_and_b32_e32 v243, 0xffff0000, v169
	v_lshlrev_b32_e32 v244, 16, v172
	v_and_b32_e32 v245, 0xffff0000, v172
	v_lshlrev_b32_e32 v246, 16, v173
	v_and_b32_e32 v247, 0xffff0000, v173
	v_pk_fma_f32 v[248:249], v[236:237], v[144:145], v[156:157]
	v_pk_fma_f32 v[236:237], v[238:239], v[146:147], v[158:159]
	v_pk_fma_f32 v[248:249], v[148:149], v[240:241], v[248:249]
	v_pk_fma_f32 v[236:237], v[150:151], v[242:243], v[236:237]
	v_pk_fma_f32 v[248:249], v[244:245], v[152:153], v[248:249]
	v_pk_fma_f32 v[236:237], v[246:247], v[154:155], v[236:237]
	v_pk_mul_f32 v[250:251], v[248:249], v[248:249]
	v_pk_mul_f32 v[252:253], v[236:237], v[236:237]
	v_pk_fma_f32 v[250:251], v[250:251], s[96:97], v[232:233] op_sel_hi:[1,0,1]
	v_pk_fma_f32 v[252:253], v[252:253], s[96:97], v[232:233] op_sel_hi:[1,0,1]
	v_pk_mul_f32 v[250:251], v[248:249], v[250:251]
	v_pk_mul_f32 v[252:253], v[236:237], v[252:253]
	v_exp_f32_e32 v250, v250
	v_exp_f32_e32 v251, v251
	v_exp_f32_e32 v252, v252
	v_exp_f32_e32 v253, v253
	v_pk_add_f32 v[250:251], v[250:251], 1.0 op_sel_hi:[1,0]
	v_pk_add_f32 v[252:253], v[252:253], 1.0 op_sel_hi:[1,0]
	v_rcp_f32_e32 v250, v250
	v_rcp_f32_e32 v251, v251
	v_rcp_f32_e32 v252, v252
	v_rcp_f32_e32 v253, v253
	v_pk_fma_f32 v[250:251], v[248:249], v[250:251], v[248:249] neg_lo:[1,0,0] neg_hi:[1,0,0]
	v_pk_fma_f32 v[252:253], v[236:237], v[252:253], v[236:237] neg_lo:[1,0,0] neg_hi:[1,0,0]
	v_pk_mul_f32 v[250:251], v[24:25], v[250:251]
	v_pk_mul_f32 v[252:253], v[26:27], v[252:253]
	v_cvt_pk_bf16_f32 v248, v250, v251
	v_cvt_pk_bf16_f32 v249, v252, v253
	ds_write_b64 v223, v[248:249] offset:33024
	v_lshlrev_b32_e32 v236, 16, v176
	v_and_b32_e32 v237, 0xffff0000, v176
	v_lshlrev_b32_e32 v238, 16, v177
	v_and_b32_e32 v239, 0xffff0000, v177
	v_lshlrev_b32_e32 v240, 16, v174
	v_and_b32_e32 v241, 0xffff0000, v174
	v_lshlrev_b32_e32 v242, 16, v175
	v_and_b32_e32 v243, 0xffff0000, v175
	v_lshlrev_b32_e32 v244, 16, v178
	v_and_b32_e32 v245, 0xffff0000, v178
	v_lshlrev_b32_e32 v246, 16, v179
	v_and_b32_e32 v247, 0xffff0000, v179
	v_pk_fma_f32 v[248:249], v[236:237], v[128:129], v[140:141]
	v_pk_fma_f32 v[236:237], v[238:239], v[130:131], v[142:143]
	v_pk_fma_f32 v[248:249], v[132:133], v[240:241], v[248:249]
	v_pk_fma_f32 v[236:237], v[134:135], v[242:243], v[236:237]
	v_pk_fma_f32 v[248:249], v[244:245], v[136:137], v[248:249]
	v_pk_fma_f32 v[236:237], v[246:247], v[138:139], v[236:237]
	v_pk_mul_f32 v[250:251], v[248:249], v[248:249]
	v_pk_mul_f32 v[252:253], v[236:237], v[236:237]
	v_pk_fma_f32 v[250:251], v[250:251], s[96:97], v[232:233] op_sel_hi:[1,0,1]
	v_pk_fma_f32 v[252:253], v[252:253], s[96:97], v[232:233] op_sel_hi:[1,0,1]
	v_pk_mul_f32 v[250:251], v[248:249], v[250:251]
	v_pk_mul_f32 v[252:253], v[236:237], v[252:253]
	v_exp_f32_e32 v250, v250
	v_exp_f32_e32 v251, v251
	v_exp_f32_e32 v252, v252
	v_exp_f32_e32 v253, v253
	v_pk_add_f32 v[250:251], v[250:251], 1.0 op_sel_hi:[1,0]
	v_pk_add_f32 v[252:253], v[252:253], 1.0 op_sel_hi:[1,0]
	v_rcp_f32_e32 v250, v250
	v_rcp_f32_e32 v251, v251
	v_rcp_f32_e32 v252, v252
	v_rcp_f32_e32 v253, v253
	v_pk_fma_f32 v[250:251], v[248:249], v[250:251], v[248:249] neg_lo:[1,0,0] neg_hi:[1,0,0]
	v_pk_fma_f32 v[252:253], v[236:237], v[252:253], v[236:237] neg_lo:[1,0,0] neg_hi:[1,0,0]
	v_pk_mul_f32 v[250:251], v[20:21], v[250:251]
	v_pk_mul_f32 v[252:253], v[22:23], v[252:253]
	v_cvt_pk_bf16_f32 v248, v250, v251
	v_cvt_pk_bf16_f32 v249, v252, v253
	ds_write_b64 v222, v[248:249] offset:40960
	v_lshlrev_b32_e32 v236, 16, v182
; #define PUT(val) *(uint2*)(g_smem + est_off(rl_, cl)) = pack4(val)
; #define STAGED2(WBODY, SBODY) { { constexpr int AIV = 0; (void)AIV; HLOOP(0, WBODY) __syncthreads(); WLOOP(0, SBODY) } __syncthreads(); { constexpr int AIV = 1; (void)AIV; HLOOP(1, WBODY) __syncthreads(); WLOOP(1, SBODY) } }
; __device__ __forceinline__ float gelu_tanh(float x) {
;   float u = 0.7978845608028654f * (x + 0.044715f * x * x * x);
;   float e = __expf(2.f * u);
;   float t = 1.f - 2.f * __builtin_amdgcn_rcpf(e + 1.f);
;   return 0.5f * x * (1.f + t);
; }
; __device__ __forceinline__ void gemm_epi(const Job& J, f32x4 (&acc)[2][2][4][2], int brow, int bcol, int wvs) {
;     ...
;   case E_UPACT: { u16* C = (u16*)J.C; const u16* G = (const u16*)J.aux; const float* cw = (const float*)J.aux2; const float* cb = (const float*)J.aux3; const int lg = J.flag;
;     STAGED2(({ int pos = R & ((1 << lg) - 1); const u16* gp = G + (long)R * DFF + Cc;
;         f32x4 g0 = unpack4(*(const uint2*)gp), gm = {0.f, 0.f, 0.f, 0.f}, gn = {0.f, 0.f, 0.f, 0.f};
;         if (pos > 0) gm = unpack4(*(const uint2*)(gp - DFF));
;         if (pos < (1 << lg) - 1) gn = unpack4(*(const uint2*)(gp + DFF));
;         f32x4 w0 = *(const f32x4*)(cw + Cc), w1 = *(const f32x4*)(cw + DFF + Cc), w2 = *(const f32x4*)(cw + 2 * DFF + Cc), bb = *(const f32x4*)(cb + Cc);
;         f32x4 o; _Pragma("unroll") for (int j = 0; j < 4; ++j) { float cv = gm[j] * w0[j] + g0[j] * w1[j] + gn[j] * w2[j] + bb[j]; o[j] = gelu_tanh(cv) * v[j]; }
;         PUT(o); }), ({ *(u32x4*)(C + (long)R * ldc + Cc) = LDV; })) } break;
	v_and_b32_e32 v237, 0xffff0000, v182
	v_lshlrev_b32_e32 v238, 16, v183
	v_and_b32_e32 v239, 0xffff0000, v183
	v_lshlrev_b32_e32 v240, 16, v180
	v_and_b32_e32 v241, 0xffff0000, v180
	v_lshlrev_b32_e32 v242, 16, v181
	v_and_b32_e32 v243, 0xffff0000, v181
	v_lshlrev_b32_e32 v244, 16, v184
	v_and_b32_e32 v245, 0xffff0000, v184
	v_lshlrev_b32_e32 v246, 16, v185
	v_and_b32_e32 v247, 0xffff0000, v185
	v_pk_fma_f32 v[248:249], v[236:237], v[144:145], v[156:157]
	v_pk_fma_f32 v[236:237], v[238:239], v[146:147], v[158:159]
	v_pk_fma_f32 v[248:249], v[148:149], v[240:241], v[248:249]
	v_pk_fma_f32 v[236:237], v[150:151], v[242:243], v[236:237]
	v_pk_fma_f32 v[248:249], v[244:245], v[152:153], v[248:249]
	v_pk_fma_f32 v[236:237], v[246:247], v[154:155], v[236:237]
	v_pk_mul_f32 v[250:251], v[248:249], v[248:249]
	v_pk_mul_f32 v[252:253], v[236:237], v[236:237]
	v_pk_fma_f32 v[250:251], v[250:251], s[96:97], v[232:233] op_sel_hi:[1,0,1]
	v_pk_fma_f32 v[252:253], v[252:253], s[96:97], v[232:233] op_sel_hi:[1,0,1]
	v_pk_mul_f32 v[250:251], v[248:249], v[250:251]
	v_pk_mul_f32 v[252:253], v[236:237], v[252:253]
	v_exp_f32_e32 v250, v250
	v_exp_f32_e32 v251, v251
	v_exp_f32_e32 v252, v252
	v_exp_f32_e32 v253, v253
	v_pk_add_f32 v[250:251], v[250:251], 1.0 op_sel_hi:[1,0]
	v_pk_add_f32 v[252:253], v[252:253], 1.0 op_sel_hi:[1,0]
	v_rcp_f32_e32 v250, v250
	v_rcp_f32_e32 v251, v251
	v_rcp_f32_e32 v252, v252
	v_rcp_f32_e32 v253, v253
	v_pk_fma_f32 v[250:251], v[248:249], v[250:251], v[248:249] neg_lo:[1,0,0] neg_hi:[1,0,0]
	v_pk_fma_f32 v[252:253], v[236:237], v[252:253], v[236:237] neg_lo:[1,0,0] neg_hi:[1,0,0]
	v_pk_mul_f32 v[250:251], v[16:17], v[250:251]
	v_pk_mul_f32 v[252:253], v[18:19], v[252:253]
	v_cvt_pk_bf16_f32 v248, v250, v251
	v_cvt_pk_bf16_f32 v249, v252, v253
	ds_write_b64 v223, v[248:249] offset:40960
	v_lshlrev_b32_e32 v236, 16, v188
	v_and_b32_e32 v237, 0xffff0000, v188
	v_lshlrev_b32_e32 v238, 16, v189
	v_and_b32_e32 v239, 0xffff0000, v189
	v_lshlrev_b32_e32 v240, 16, v186
	v_and_b32_e32 v241, 0xffff0000, v186
	v_lshlrev_b32_e32 v242, 16, v187
	v_and_b32_e32 v243, 0xffff0000, v187
	v_lshlrev_b32_e32 v244, 16, v190
	v_and_b32_e32 v245, 0xffff0000, v190
	v_lshlrev_b32_e32 v246, 16, v191
	v_and_b32_e32 v247, 0xffff0000, v191
	v_pk_fma_f32 v[248:249], v[236:237], v[128:129], v[140:141]
	v_pk_fma_f32 v[236:237], v[238:239], v[130:131], v[142:143]
	v_pk_fma_f32 v[248:249], v[132:133], v[240:241], v[248:249]
	v_pk_fma_f32 v[236:237], v[134:135], v[242:243], v[236:237]
	v_pk_fma_f32 v[248:249], v[244:245], v[136:137], v[248:249]
	v_pk_fma_f32 v[236:237], v[246:247], v[138:139], v[236:237]
	v_pk_mul_f32 v[250:251], v[248:249], v[248:249]
	v_pk_mul_f32 v[252:253], v[236:237], v[236:237]
	v_pk_fma_f32 v[250:251], v[250:251], s[96:97], v[232:233] op_sel_hi:[1,0,1]
	v_pk_fma_f32 v[252:253], v[252:253], s[96:97], v[232:233] op_sel_hi:[1,0,1]
	v_pk_mul_f32 v[250:251], v[248:249], v[250:251]
	v_pk_mul_f32 v[252:253], v[236:237], v[252:253]
	v_exp_f32_e32 v250, v250
	v_exp_f32_e32 v251, v251
	v_exp_f32_e32 v252, v252
	v_exp_f32_e32 v253, v253
	v_pk_add_f32 v[250:251], v[250:251], 1.0 op_sel_hi:[1,0]
	v_pk_add_f32 v[252:253], v[252:253], 1.0 op_sel_hi:[1,0]
	v_rcp_f32_e32 v250, v250
	v_rcp_f32_e32 v251, v251
	v_rcp_f32_e32 v252, v252
	v_rcp_f32_e32 v253, v253
	v_pk_fma_f32 v[250:251], v[248:249], v[250:251], v[248:249] neg_lo:[1,0,0] neg_hi:[1,0,0]
	v_pk_fma_f32 v[252:253], v[236:237], v[252:253], v[236:237] neg_lo:[1,0,0] neg_hi:[1,0,0]
	v_pk_mul_f32 v[250:251], v[12:13], v[250:251]
	v_pk_mul_f32 v[252:253], v[14:15], v[252:253]
	v_cvt_pk_bf16_f32 v248, v250, v251
	v_cvt_pk_bf16_f32 v249, v252, v253
	ds_write_b64 v222, v[248:249] offset:49408
	v_lshlrev_b32_e32 v236, 16, v194
	v_and_b32_e32 v237, 0xffff0000, v194
	v_lshlrev_b32_e32 v238, 16, v195
	v_and_b32_e32 v239, 0xffff0000, v195
	v_lshlrev_b32_e32 v240, 16, v192
	v_and_b32_e32 v241, 0xffff0000, v192
	v_lshlrev_b32_e32 v242, 16, v193
	v_and_b32_e32 v243, 0xffff0000, v193
	v_lshlrev_b32_e32 v244, 16, v196
	v_and_b32_e32 v245, 0xffff0000, v196
	v_lshlrev_b32_e32 v246, 16, v197
	v_and_b32_e32 v247, 0xffff0000, v197
	v_pk_fma_f32 v[248:249], v[236:237], v[144:145], v[156:157]
	v_pk_fma_f32 v[236:237], v[238:239], v[146:147], v[158:159]
	v_pk_fma_f32 v[248:249], v[148:149], v[240:241], v[248:249]
	v_pk_fma_f32 v[236:237], v[150:151], v[242:243], v[236:237]
	v_pk_fma_f32 v[248:249], v[244:245], v[152:153], v[248:249]
	v_pk_fma_f32 v[236:237], v[246:247], v[154:155], v[236:237]
	v_pk_mul_f32 v[250:251], v[248:249], v[248:249]
	v_pk_mul_f32 v[252:253], v[236:237], v[236:237]
	v_pk_fma_f32 v[250:251], v[250:251], s[96:97], v[232:233] op_sel_hi:[1,0,1]
	v_pk_fma_f32 v[252:253], v[252:253], s[96:97], v[232:233] op_sel_hi:[1,0,1]
	v_pk_mul_f32 v[250:251], v[248:249], v[250:251]
	v_pk_mul_f32 v[252:253], v[236:237], v[252:253]
	v_exp_f32_e32 v250, v250
	v_exp_f32_e32 v251, v251
	v_exp_f32_e32 v252, v252
	v_exp_f32_e32 v253, v253
	v_pk_add_f32 v[250:251], v[250:251], 1.0 op_sel_hi:[1,0]
	v_pk_add_f32 v[252:253], v[252:253], 1.0 op_sel_hi:[1,0]
	v_rcp_f32_e32 v250, v250
	v_rcp_f32_e32 v251, v251
	v_rcp_f32_e32 v252, v252
	v_rcp_f32_e32 v253, v253
	v_pk_fma_f32 v[250:251], v[248:249], v[250:251], v[248:249] neg_lo:[1,0,0] neg_hi:[1,0,0]
	v_pk_fma_f32 v[252:253], v[236:237], v[252:253], v[236:237] neg_lo:[1,0,0] neg_hi:[1,0,0]
	v_pk_mul_f32 v[250:251], v[8:9], v[250:251]
	v_pk_mul_f32 v[252:253], v[10:11], v[252:253]
	v_cvt_pk_bf16_f32 v248, v250, v251
	v_cvt_pk_bf16_f32 v249, v252, v253
	ds_write_b64 v223, v[248:249] offset:49408
	v_add_u32_e32 v228, 176, v224
	v_and_b32_e32 v228, s31, v228
	v_cmp_ne_u32_e32 vcc, s31, v228
; #define PUT(val) *(uint2*)(g_smem + est_off(rl_, cl)) = pack4(val)
; #define STAGED2(WBODY, SBODY) { { constexpr int AIV = 0; (void)AIV; HLOOP(0, WBODY) __syncthreads(); WLOOP(0, SBODY) } __syncthreads(); { constexpr int AIV = 1; (void)AIV; HLOOP(1, WBODY) __syncthreads(); WLOOP(1, SBODY) } }
; __device__ __forceinline__ void gemm_epi(const Job& J, f32x4 (&acc)[2][2][4][2], int brow, int bcol, int wvs) {
;     ...
;   switch (mode) {
;   case E_UPACT: { u16* C = (u16*)J.C; const u16* G = (const u16*)J.aux; const float* cw = (const float*)J.aux2; const float* cb = (const float*)J.aux3; const int lg = J.flag;
;     STAGED2(({ int pos = R & ((1 << lg) - 1); const u16* gp = G + (long)R * DFF + Cc;
;         f32x4 g0 = unpack4(*(const uint2*)gp), gm = {0.f, 0.f, 0.f, 0.f}, gn = {0.f, 0.f, 0.f, 0.f};
;         if (pos > 0) gm = unpack4(*(const uint2*)(gp - DFF));
;         if (pos < (1 << lg) - 1) gn = unpack4(*(const uint2*)(gp + DFF));
;         f32x4 w0 = *(const f32x4*)(cw + Cc), w1 = *(const f32x4*)(cw + DFF + Cc), w2 = *(const f32x4*)(cw + 2 * DFF + Cc), bb = *(const f32x4*)(cb + Cc);
;         f32x4 o; _Pragma("unroll") for (int j = 0; j < 4; ++j) { float cv = gm[j] * w0[j] + g0[j] * w1[j] + gn[j] * w2[j] + bb[j]; o[j] = gelu_tanh(cv) * v[j]; }
;         PUT(o); }), ({ *(u32x4*)(C + (long)R * ldc + Cc) = LDV; })) } break;
	s_nop 1
	v_cndmask_b32_e64 v226, 0, -1, vcc
	v_and_b32_e32 v202, v226, v202
	v_and_b32_e32 v203, v226, v203
	v_lshlrev_b32_e32 v236, 16, v200
	v_and_b32_e32 v237, 0xffff0000, v200
	v_lshlrev_b32_e32 v238, 16, v201
	v_and_b32_e32 v239, 0xffff0000, v201
	v_lshlrev_b32_e32 v240, 16, v198
	v_and_b32_e32 v241, 0xffff0000, v198
	v_lshlrev_b32_e32 v242, 16, v199
	v_and_b32_e32 v243, 0xffff0000, v199
	v_lshlrev_b32_e32 v244, 16, v202
	v_and_b32_e32 v245, 0xffff0000, v202
	v_lshlrev_b32_e32 v246, 16, v203
	v_and_b32_e32 v247, 0xffff0000, v203
	v_pk_fma_f32 v[248:249], v[236:237], v[128:129], v[140:141]
	v_pk_fma_f32 v[236:237], v[238:239], v[130:131], v[142:143]
	v_pk_fma_f32 v[248:249], v[132:133], v[240:241], v[248:249]
	v_pk_fma_f32 v[236:237], v[134:135], v[242:243], v[236:237]
	v_pk_fma_f32 v[248:249], v[244:245], v[136:137], v[248:249]
	v_pk_fma_f32 v[236:237], v[246:247], v[138:139], v[236:237]
	v_pk_mul_f32 v[250:251], v[248:249], v[248:249]
	v_pk_mul_f32 v[252:253], v[236:237], v[236:237]
	v_pk_fma_f32 v[250:251], v[250:251], s[96:97], v[232:233] op_sel_hi:[1,0,1]
	v_pk_fma_f32 v[252:253], v[252:253], s[96:97], v[232:233] op_sel_hi:[1,0,1]
	v_pk_mul_f32 v[250:251], v[248:249], v[250:251]
	v_pk_mul_f32 v[252:253], v[236:237], v[252:253]
	v_exp_f32_e32 v250, v250
	v_exp_f32_e32 v251, v251
	v_exp_f32_e32 v252, v252
	v_exp_f32_e32 v253, v253
	v_pk_add_f32 v[250:251], v[250:251], 1.0 op_sel_hi:[1,0]
	v_pk_add_f32 v[252:253], v[252:253], 1.0 op_sel_hi:[1,0]
	v_rcp_f32_e32 v250, v250
	v_rcp_f32_e32 v251, v251
	v_rcp_f32_e32 v252, v252
	v_rcp_f32_e32 v253, v253
	v_pk_fma_f32 v[250:251], v[248:249], v[250:251], v[248:249] neg_lo:[1,0,0] neg_hi:[1,0,0]
	v_pk_fma_f32 v[252:253], v[236:237], v[252:253], v[236:237] neg_lo:[1,0,0] neg_hi:[1,0,0]
	v_pk_mul_f32 v[250:251], v[4:5], v[250:251]
	v_pk_mul_f32 v[252:253], v[6:7], v[252:253]
	v_cvt_pk_bf16_f32 v248, v250, v251
	v_cvt_pk_bf16_f32 v249, v252, v253
	ds_write_b64 v222, v[248:249] offset:57344
	v_and_b32_e32 v218, v226, v218
	v_and_b32_e32 v219, v226, v219
	v_lshlrev_b32_e32 v236, 16, v216
	v_and_b32_e32 v237, 0xffff0000, v216
	v_lshlrev_b32_e32 v238, 16, v217
	v_and_b32_e32 v239, 0xffff0000, v217
	v_lshlrev_b32_e32 v240, 16, v214
	v_and_b32_e32 v241, 0xffff0000, v214
	v_lshlrev_b32_e32 v242, 16, v215
	v_and_b32_e32 v243, 0xffff0000, v215
	v_lshlrev_b32_e32 v244, 16, v218
	v_and_b32_e32 v245, 0xffff0000, v218
	v_lshlrev_b32_e32 v246, 16, v219
	v_and_b32_e32 v247, 0xffff0000, v219
	v_pk_fma_f32 v[248:249], v[236:237], v[144:145], v[156:157]
	v_pk_fma_f32 v[236:237], v[238:239], v[146:147], v[158:159]
	v_pk_fma_f32 v[248:249], v[148:149], v[240:241], v[248:249]
	v_pk_fma_f32 v[236:237], v[150:151], v[242:243], v[236:237]
	v_pk_fma_f32 v[248:249], v[244:245], v[152:153], v[248:249]
	v_pk_fma_f32 v[236:237], v[246:247], v[154:155], v[236:237]
	v_pk_mul_f32 v[250:251], v[248:249], v[248:249]
	v_pk_mul_f32 v[252:253], v[236:237], v[236:237]
	v_pk_fma_f32 v[250:251], v[250:251], s[96:97], v[232:233] op_sel_hi:[1,0,1]
	v_pk_fma_f32 v[252:253], v[252:253], s[96:97], v[232:233] op_sel_hi:[1,0,1]
	v_pk_mul_f32 v[250:251], v[248:249], v[250:251]
	v_pk_mul_f32 v[252:253], v[236:237], v[252:253]
	v_exp_f32_e32 v250, v250
	v_exp_f32_e32 v251, v251
	v_exp_f32_e32 v252, v252
	v_exp_f32_e32 v253, v253
	v_pk_add_f32 v[250:251], v[250:251], 1.0 op_sel_hi:[1,0]
	v_pk_add_f32 v[252:253], v[252:253], 1.0 op_sel_hi:[1,0]
	v_rcp_f32_e32 v250, v250
	v_rcp_f32_e32 v251, v251
	v_rcp_f32_e32 v252, v252
	v_rcp_f32_e32 v253, v253
	v_pk_fma_f32 v[250:251], v[248:249], v[250:251], v[248:249] neg_lo:[1,0,0] neg_hi:[1,0,0]
	v_pk_fma_f32 v[252:253], v[236:237], v[252:253], v[236:237] neg_lo:[1,0,0] neg_hi:[1,0,0]
	v_pk_mul_f32 v[250:251], v[0:1], v[250:251]
	v_pk_mul_f32 v[252:253], v[2:3], v[252:253]
	v_cvt_pk_bf16_f32 v248, v250, v251
	v_cvt_pk_bf16_f32 v249, v252, v253
	ds_write_b64 v223, v[248:249] offset:57344
	s_waitcnt lgkmcnt(0)
	s_barrier
	v_add_u32_e32 v99, s69, v210
	v_lshrrev_b32_e32 v99, 5, v99
	v_and_b32_e32 v98, 31, v210
	v_xor_b32_e32 v96, v98, v99
	v_lshlrev_b32_e32 v96, 4, v96
	v_xor_b32_e32 v97, 0x100, v96
	v_lshl_add_u32 v96, v99, 9, v96
	v_lshl_add_u32 v97, v99, 9, v97
	v_mul_u32_u24_e32 v99, s4, v99
	v_lshlrev_b32_e32 v98, 4, v98
	v_lshl_add_u32 v98, v99, 1, v98
	s_mul_i32 s6, s84, s4
	s_add_i32 s6, s6, s22
	s_lshl_b32 s6, s6, 1
	s_add_u32 s6, s26, s6
	s_addc_u32 s7, s27, 0
	s_lshl_b32 s8, s4, 5
	ds_read_b128 v[64:67], v96 offset:32768
	ds_read_b128 v[68:71], v97 offset:40960
	ds_read_b128 v[72:75], v96 offset:49152
	ds_read_b128 v[76:79], v97 offset:57344
	v_add_u32_e32 v96, 0x10000, v96
	v_add_u32_e32 v97, 0x10000, v97
	ds_read_b128 v[80:83], v96 offset:32768
	ds_read_b128 v[84:87], v97 offset:40960
	ds_read_b128 v[88:91], v96 offset:49152
	ds_read_b128 v[92:95], v97 offset:57344
	s_waitcnt lgkmcnt(7)
	global_store_dwordx4 v98, v[64:67], s[6:7]
	s_add_u32 s6, s6, s8
	s_addc_u32 s7, s7, 0
	s_waitcnt lgkmcnt(6)
	global_store_dwordx4 v98, v[68:71], s[6:7]
	s_add_u32 s6, s6, s8
	s_addc_u32 s7, s7, 0
	s_waitcnt lgkmcnt(5)
	global_store_dwordx4 v98, v[72:75], s[6:7]
	s_add_u32 s6, s6, s8
	s_addc_u32 s7, s7, 0
	s_waitcnt lgkmcnt(4)
	global_store_dwordx4 v98, v[76:79], s[6:7]
	s_add_u32 s6, s6, s8
	s_addc_u32 s7, s7, 0
	s_waitcnt lgkmcnt(3)
	global_store_dwordx4 v98, v[80:83], s[6:7]
	s_add_u32 s6, s6, s8
	s_addc_u32 s7, s7, 0
	s_waitcnt lgkmcnt(2)
	global_store_dwordx4 v98, v[84:87], s[6:7]
	s_add_u32 s6, s6, s8
	s_addc_u32 s7, s7, 0
	s_waitcnt lgkmcnt(1)
	global_store_dwordx4 v98, v[88:91], s[6:7]
	s_add_u32 s6, s6, s8
	s_addc_u32 s7, s7, 0
	s_waitcnt lgkmcnt(0)
	global_store_dwordx4 v98, v[92:95], s[6:7]
	s_mov_b64 s[8:9], 0
